# v16: back-edge rotation (7.11) in the 8 GEMM K loops: counter/pointer SALU block moved from after the last barrier to the start of the last compute segment
# baseline (speedup 1.0000x reference)
.LBB0_193:
	ds_read_b128 v[130:133], v169
	ds_read_b128 v[134:137], v169 offset:1024
	ds_read_b128 v[138:141], v169 offset:2048
	ds_read_b128 v[142:145], v169 offset:3072
	ds_read_b128 v[170:173], v174
	ds_read_b128 v[180:183], v174 offset:1024
	ds_read_b128 v[184:187], v174 offset:2048
	ds_read_b128 v[188:191], v174 offset:3072
	s_add_u32 s30, s4, 0xfffc0080
	s_addc_u32 s31, s5, -1
	s_cmp_eq_u32 s54, 12
	s_cselect_b32 s35, s23, s31
	s_cselect_b32 s34, s38, s30
	s_cselect_b32 s31, s21, s53
	s_cselect_b32 s30, s39, s52
	v_lshl_add_u64 v[166:167], s[4:5], 0, v[158:159]
	s_add_i32 m0, s47, 0xc000
	ds_read_b128 v[192:195], v175
	ds_read_b128 v[196:199], v175 offset:1024
	ds_read_b128 v[200:203], v175 offset:2048
	ds_read_b128 v[204:207], v175 offset:3072
	ds_read_b128 v[208:211], v175 offset:4096
	ds_read_b128 v[212:215], v175 offset:5120
	ds_read_b128 v[216:219], v175 offset:6144
	ds_read_b128 v[220:223], v175 offset:7168
	global_load_lds_dwordx4 v[166:167], off
	v_lshl_add_u64 v[166:167], s[4:5], 0, v[160:161]
	s_add_i32 m0, s47, 0xe000
	s_nop 0
	global_load_lds_dwordx4 v[166:167], off
	s_waitcnt vmcnt(8)
	s_waitcnt lgkmcnt(0)
	s_barrier
	s_setprio 1
	s_waitcnt lgkmcnt(0)
	v_mfma_f32_16x16x32_bf16 v[126:129], v[130:133], v[192:195], v[126:129]
	v_mfma_f32_16x16x32_bf16 v[122:125], v[138:141], v[192:195], v[122:125]
	v_mfma_f32_16x16x32_bf16 v[110:113], v[130:133], v[200:203], v[110:113]
	v_mfma_f32_16x16x32_bf16 v[106:109], v[138:141], v[200:203], v[106:109]
	v_mfma_f32_16x16x32_bf16 v[94:97], v[130:133], v[208:211], v[94:97]
	v_mfma_f32_16x16x32_bf16 v[90:93], v[138:141], v[208:211], v[90:93]
	v_mfma_f32_16x16x32_bf16 v[78:81], v[130:133], v[216:219], v[78:81]
	v_mfma_f32_16x16x32_bf16 v[74:77], v[138:141], v[216:219], v[74:77]
	v_mfma_f32_16x16x32_bf16 v[126:129], v[134:137], v[196:199], v[126:129]
	v_mfma_f32_16x16x32_bf16 v[122:125], v[142:145], v[196:199], v[122:125]
	v_mfma_f32_16x16x32_bf16 v[110:113], v[134:137], v[204:207], v[110:113]
	v_mfma_f32_16x16x32_bf16 v[106:109], v[142:145], v[204:207], v[106:109]
	v_mfma_f32_16x16x32_bf16 v[94:97], v[134:137], v[212:215], v[94:97]
	v_mfma_f32_16x16x32_bf16 v[90:93], v[142:145], v[212:215], v[90:93]
	v_mfma_f32_16x16x32_bf16 v[78:81], v[134:137], v[220:223], v[78:81]
	v_mfma_f32_16x16x32_bf16 v[74:77], v[142:145], v[220:223], v[74:77]
	s_setprio 0
	s_setprio 1
	v_mfma_f32_16x16x32_bf16 v[118:121], v[170:173], v[192:195], v[118:121]
	v_mfma_f32_16x16x32_bf16 v[114:117], v[184:187], v[192:195], v[114:117]
	v_mfma_f32_16x16x32_bf16 v[102:105], v[170:173], v[200:203], v[102:105]
	v_mfma_f32_16x16x32_bf16 v[98:101], v[184:187], v[200:203], v[98:101]
	v_mfma_f32_16x16x32_bf16 v[86:89], v[170:173], v[208:211], v[86:89]
	v_mfma_f32_16x16x32_bf16 v[82:85], v[184:187], v[208:211], v[82:85]
	v_mfma_f32_16x16x32_bf16 v[70:73], v[170:173], v[216:219], v[70:73]
	v_mfma_f32_16x16x32_bf16 v[66:69], v[184:187], v[216:219], v[66:69]
	v_mfma_f32_16x16x32_bf16 v[118:121], v[180:183], v[196:199], v[118:121]
	v_mfma_f32_16x16x32_bf16 v[114:117], v[188:191], v[196:199], v[114:117]
	v_mfma_f32_16x16x32_bf16 v[102:105], v[180:183], v[204:207], v[102:105]
	v_mfma_f32_16x16x32_bf16 v[98:101], v[188:191], v[204:207], v[98:101]
	v_mfma_f32_16x16x32_bf16 v[86:89], v[180:183], v[212:215], v[86:89]
	v_mfma_f32_16x16x32_bf16 v[82:85], v[188:191], v[212:215], v[82:85]
	v_mfma_f32_16x16x32_bf16 v[70:73], v[180:183], v[220:223], v[70:73]
	v_mfma_f32_16x16x32_bf16 v[66:69], v[188:191], v[220:223], v[66:69]
	s_setprio 0
	s_barrier
	s_add_i32 s55, s64, s44
	v_lshl_add_u64 v[166:167], s[30:31], 0, v[148:149]
	s_mov_b32 m0, s55
	ds_read_b128 v[192:195], v175 offset:16384
	ds_read_b128 v[196:199], v175 offset:17408
	ds_read_b128 v[200:203], v175 offset:18432
	ds_read_b128 v[204:207], v175 offset:19456
	ds_read_b128 v[208:211], v175 offset:20480
	ds_read_b128 v[212:215], v175 offset:21504
	ds_read_b128 v[216:219], v175 offset:22528
	ds_read_b128 v[220:223], v175 offset:23552
	global_load_lds_dwordx4 v[166:167], off
	s_add_i32 m0, s55, 0x2000
	s_add_u32 s76, s30, 0x40000
	v_lshl_add_u64 v[224:225], s[30:31], 0, v[146:147]
	s_addc_u32 s77, s31, 0
	s_add_i32 s55, s65, s44
	global_load_lds_dwordx4 v[224:225], off
	v_lshl_add_u64 v[226:227], s[76:77], 0, v[148:149]
	s_mov_b32 m0, s55
	v_lshl_add_u64 v[228:229], s[34:35], 0, v[146:147]
	global_load_lds_dwordx4 v[226:227], off
	v_lshl_add_u64 v[226:227], s[76:77], 0, v[146:147]
	s_add_i32 m0, s55, 0x2000
	s_nop 0
	global_load_lds_dwordx4 v[226:227], off
	v_lshl_add_u64 v[226:227], s[34:35], 0, v[148:149]
	s_mov_b32 m0, s47
	s_nop 0
	global_load_lds_dwordx4 v[226:227], off
	s_mov_b32 m0, s36
	s_nop 0
	global_load_lds_dwordx4 v[228:229], off
	s_waitcnt vmcnt(8)
	s_waitcnt lgkmcnt(0)
	s_barrier
	s_setprio 1
	s_waitcnt lgkmcnt(0)
	v_mfma_f32_16x16x32_bf16 v[62:65], v[130:133], v[192:195], v[62:65]
	v_mfma_f32_16x16x32_bf16 v[58:61], v[138:141], v[192:195], v[58:61]
	v_mfma_f32_16x16x32_bf16 v[46:49], v[130:133], v[200:203], v[46:49]
	v_mfma_f32_16x16x32_bf16 v[42:45], v[138:141], v[200:203], v[42:45]
	v_mfma_f32_16x16x32_bf16 v[30:33], v[130:133], v[208:211], v[30:33]
	v_mfma_f32_16x16x32_bf16 v[26:29], v[138:141], v[208:211], v[26:29]
	v_mfma_f32_16x16x32_bf16 v[14:17], v[130:133], v[216:219], v[14:17]
	v_mfma_f32_16x16x32_bf16 v[10:13], v[138:141], v[216:219], v[10:13]
	v_mfma_f32_16x16x32_bf16 v[62:65], v[134:137], v[196:199], v[62:65]
	v_mfma_f32_16x16x32_bf16 v[58:61], v[142:145], v[196:199], v[58:61]
	v_mfma_f32_16x16x32_bf16 v[46:49], v[134:137], v[204:207], v[46:49]
	v_mfma_f32_16x16x32_bf16 v[42:45], v[142:145], v[204:207], v[42:45]
	v_mfma_f32_16x16x32_bf16 v[30:33], v[134:137], v[212:215], v[30:33]
	v_mfma_f32_16x16x32_bf16 v[26:29], v[142:145], v[212:215], v[26:29]
	v_mfma_f32_16x16x32_bf16 v[14:17], v[134:137], v[220:223], v[14:17]
	v_mfma_f32_16x16x32_bf16 v[10:13], v[142:145], v[220:223], v[10:13]
	s_setprio 0
	s_setprio 1
	v_mfma_f32_16x16x32_bf16 v[54:57], v[170:173], v[192:195], v[54:57]
	v_mfma_f32_16x16x32_bf16 v[50:53], v[184:187], v[192:195], v[50:53]
	v_mfma_f32_16x16x32_bf16 v[38:41], v[170:173], v[200:203], v[38:41]
	v_mfma_f32_16x16x32_bf16 v[34:37], v[184:187], v[200:203], v[34:37]
	v_mfma_f32_16x16x32_bf16 v[22:25], v[170:173], v[208:211], v[22:25]
	v_mfma_f32_16x16x32_bf16 v[18:21], v[184:187], v[208:211], v[18:21]
	v_mfma_f32_16x16x32_bf16 v[6:9], v[170:173], v[216:219], v[6:9]
	v_mfma_f32_16x16x32_bf16 v[2:5], v[184:187], v[216:219], v[2:5]
	v_mfma_f32_16x16x32_bf16 v[54:57], v[180:183], v[196:199], v[54:57]
	v_mfma_f32_16x16x32_bf16 v[50:53], v[188:191], v[196:199], v[50:53]
	v_mfma_f32_16x16x32_bf16 v[38:41], v[180:183], v[204:207], v[38:41]
	v_mfma_f32_16x16x32_bf16 v[34:37], v[188:191], v[204:207], v[34:37]
	v_mfma_f32_16x16x32_bf16 v[22:25], v[180:183], v[212:215], v[22:25]
	v_mfma_f32_16x16x32_bf16 v[18:21], v[188:191], v[212:215], v[18:21]
	v_mfma_f32_16x16x32_bf16 v[6:9], v[180:183], v[220:223], v[6:9]
	v_mfma_f32_16x16x32_bf16 v[2:5], v[188:191], v[220:223], v[2:5]
	s_setprio 0
	s_barrier
	s_add_i32 s55, 0, 0x18000
	s_add_i32 s76, 0, 0x1c000
	v_add_u32_e32 v142, s55, v153
	v_add_u32_e32 v150, s76, v153
	ds_read_b128 v[130:133], v142
	ds_read_b128 v[134:137], v142 offset:1024
	ds_read_b128 v[138:141], v142 offset:2048
	ds_read_b128 v[142:145], v142 offset:3072
	ds_read_b128 v[170:173], v150
	ds_read_b128 v[180:183], v150 offset:1024
	ds_read_b128 v[184:187], v150 offset:2048
	ds_read_b128 v[188:191], v150 offset:3072
	s_add_u32 s34, s34, 0x40000
	s_addc_u32 s35, s35, 0
	s_mov_b32 m0, s37
	v_lshl_add_u64 v[230:231], s[34:35], 0, v[148:149]
	ds_read_b128 v[192:195], v175 offset:32768
	ds_read_b128 v[196:199], v175 offset:33792
	ds_read_b128 v[200:203], v175 offset:34816
	ds_read_b128 v[204:207], v175 offset:35840
	ds_read_b128 v[208:211], v175 offset:36864
	ds_read_b128 v[212:215], v175 offset:37888
	ds_read_b128 v[216:219], v175 offset:38912
	ds_read_b128 v[220:223], v175 offset:39936
	global_load_lds_dwordx4 v[230:231], off
	v_lshl_add_u64 v[230:231], s[34:35], 0, v[146:147]
	s_mov_b32 m0, s42
	s_nop 0
	global_load_lds_dwordx4 v[230:231], off
	s_waitcnt vmcnt(8)
	s_waitcnt lgkmcnt(0)
	s_barrier
	s_setprio 1
	s_waitcnt lgkmcnt(0)
	v_mfma_f32_16x16x32_bf16 v[126:129], v[130:133], v[192:195], v[126:129]
	v_mfma_f32_16x16x32_bf16 v[122:125], v[138:141], v[192:195], v[122:125]
	v_mfma_f32_16x16x32_bf16 v[110:113], v[130:133], v[200:203], v[110:113]
	v_mfma_f32_16x16x32_bf16 v[106:109], v[138:141], v[200:203], v[106:109]
	v_mfma_f32_16x16x32_bf16 v[94:97], v[130:133], v[208:211], v[94:97]
	v_mfma_f32_16x16x32_bf16 v[90:93], v[138:141], v[208:211], v[90:93]
	v_mfma_f32_16x16x32_bf16 v[78:81], v[130:133], v[216:219], v[78:81]
	v_mfma_f32_16x16x32_bf16 v[74:77], v[138:141], v[216:219], v[74:77]
	v_mfma_f32_16x16x32_bf16 v[126:129], v[134:137], v[196:199], v[126:129]
	v_mfma_f32_16x16x32_bf16 v[122:125], v[142:145], v[196:199], v[122:125]
	v_mfma_f32_16x16x32_bf16 v[110:113], v[134:137], v[204:207], v[110:113]
	v_mfma_f32_16x16x32_bf16 v[106:109], v[142:145], v[204:207], v[106:109]
	v_mfma_f32_16x16x32_bf16 v[94:97], v[134:137], v[212:215], v[94:97]
	v_mfma_f32_16x16x32_bf16 v[90:93], v[142:145], v[212:215], v[90:93]
	v_mfma_f32_16x16x32_bf16 v[78:81], v[134:137], v[220:223], v[78:81]
	v_mfma_f32_16x16x32_bf16 v[74:77], v[142:145], v[220:223], v[74:77]
	s_setprio 0
	s_setprio 1
	v_mfma_f32_16x16x32_bf16 v[118:121], v[170:173], v[192:195], v[118:121]
	v_mfma_f32_16x16x32_bf16 v[114:117], v[184:187], v[192:195], v[114:117]
	v_mfma_f32_16x16x32_bf16 v[102:105], v[170:173], v[200:203], v[102:105]
	v_mfma_f32_16x16x32_bf16 v[98:101], v[184:187], v[200:203], v[98:101]
	v_mfma_f32_16x16x32_bf16 v[86:89], v[170:173], v[208:211], v[86:89]
	v_mfma_f32_16x16x32_bf16 v[82:85], v[184:187], v[208:211], v[82:85]
	v_mfma_f32_16x16x32_bf16 v[70:73], v[170:173], v[216:219], v[70:73]
	v_mfma_f32_16x16x32_bf16 v[66:69], v[184:187], v[216:219], v[66:69]
	v_mfma_f32_16x16x32_bf16 v[118:121], v[180:183], v[196:199], v[118:121]
	v_mfma_f32_16x16x32_bf16 v[114:117], v[188:191], v[196:199], v[114:117]
	v_mfma_f32_16x16x32_bf16 v[102:105], v[180:183], v[204:207], v[102:105]
	v_mfma_f32_16x16x32_bf16 v[98:101], v[188:191], v[204:207], v[98:101]
	v_mfma_f32_16x16x32_bf16 v[86:89], v[180:183], v[212:215], v[86:89]
	v_mfma_f32_16x16x32_bf16 v[82:85], v[188:191], v[212:215], v[82:85]
	v_mfma_f32_16x16x32_bf16 v[70:73], v[180:183], v[220:223], v[70:73]
	v_mfma_f32_16x16x32_bf16 v[66:69], v[188:191], v[220:223], v[66:69]
	s_setprio 0
	s_barrier
	s_add_i32 s34, s55, s44
	v_lshl_add_u64 v[166:167], v[166:167], 0, s[14:15]
	s_mov_b32 m0, s34
	ds_read_b128 v[192:195], v175 offset:49152
	ds_read_b128 v[196:199], v175 offset:50176
	ds_read_b128 v[200:203], v175 offset:51200
	ds_read_b128 v[204:207], v175 offset:52224
	ds_read_b128 v[208:211], v175 offset:53248
	ds_read_b128 v[212:215], v175 offset:54272
	ds_read_b128 v[216:219], v175 offset:55296
	ds_read_b128 v[220:223], v175 offset:56320
	global_load_lds_dwordx4 v[166:167], off
	s_add_i32 m0, s34, 0x2000
	s_add_u32 s30, s30, 0x40080
	v_lshl_add_u64 v[166:167], v[224:225], 0, s[14:15]
	s_addc_u32 s31, s31, 0
	s_add_i32 s34, s76, s44
	global_load_lds_dwordx4 v[166:167], off
	v_lshl_add_u64 v[166:167], s[30:31], 0, v[148:149]
	s_mov_b32 m0, s34
	s_nop 0
	global_load_lds_dwordx4 v[166:167], off
	v_lshl_add_u64 v[166:167], s[30:31], 0, v[146:147]
	s_add_i32 m0, s34, 0x2000
	s_nop 0
	global_load_lds_dwordx4 v[166:167], off
	v_lshl_add_u64 v[166:167], v[226:227], 0, s[14:15]
	s_mov_b32 m0, s43
	s_nop 0
	global_load_lds_dwordx4 v[166:167], off
	v_lshl_add_u64 v[166:167], v[228:229], 0, s[14:15]
	s_mov_b32 m0, s78
	s_nop 0
	global_load_lds_dwordx4 v[166:167], off
	s_waitcnt vmcnt(8)
	s_waitcnt lgkmcnt(0)
	s_barrier
	s_add_i32 s54, s54, 2
	s_add_u32 s4, s4, 0x100
	s_addc_u32 s5, s5, 0
	s_add_u32 s52, s52, 0x100
	s_addc_u32 s53, s53, 0
	s_cmp_gt_u32 s54, 13
	s_setprio 1
	s_waitcnt lgkmcnt(0)
	v_mfma_f32_16x16x32_bf16 v[62:65], v[130:133], v[192:195], v[62:65]
	v_mfma_f32_16x16x32_bf16 v[58:61], v[138:141], v[192:195], v[58:61]
	v_mfma_f32_16x16x32_bf16 v[46:49], v[130:133], v[200:203], v[46:49]
	v_mfma_f32_16x16x32_bf16 v[42:45], v[138:141], v[200:203], v[42:45]
	v_mfma_f32_16x16x32_bf16 v[30:33], v[130:133], v[208:211], v[30:33]
	v_mfma_f32_16x16x32_bf16 v[26:29], v[138:141], v[208:211], v[26:29]
	v_mfma_f32_16x16x32_bf16 v[14:17], v[130:133], v[216:219], v[14:17]
	v_mfma_f32_16x16x32_bf16 v[10:13], v[138:141], v[216:219], v[10:13]
	v_mfma_f32_16x16x32_bf16 v[62:65], v[134:137], v[196:199], v[62:65]
	v_mfma_f32_16x16x32_bf16 v[58:61], v[142:145], v[196:199], v[58:61]
	v_mfma_f32_16x16x32_bf16 v[46:49], v[134:137], v[204:207], v[46:49]
	v_mfma_f32_16x16x32_bf16 v[42:45], v[142:145], v[204:207], v[42:45]
	v_mfma_f32_16x16x32_bf16 v[30:33], v[134:137], v[212:215], v[30:33]
	v_mfma_f32_16x16x32_bf16 v[26:29], v[142:145], v[212:215], v[26:29]
	v_mfma_f32_16x16x32_bf16 v[14:17], v[134:137], v[220:223], v[14:17]
	v_mfma_f32_16x16x32_bf16 v[10:13], v[142:145], v[220:223], v[10:13]
	s_setprio 0
	s_setprio 1
	v_mfma_f32_16x16x32_bf16 v[54:57], v[170:173], v[192:195], v[54:57]
	v_mfma_f32_16x16x32_bf16 v[50:53], v[184:187], v[192:195], v[50:53]
	v_mfma_f32_16x16x32_bf16 v[38:41], v[170:173], v[200:203], v[38:41]
	v_mfma_f32_16x16x32_bf16 v[34:37], v[184:187], v[200:203], v[34:37]
	v_mfma_f32_16x16x32_bf16 v[22:25], v[170:173], v[208:211], v[22:25]
	v_mfma_f32_16x16x32_bf16 v[18:21], v[184:187], v[208:211], v[18:21]
	v_mfma_f32_16x16x32_bf16 v[6:9], v[170:173], v[216:219], v[6:9]
	v_mfma_f32_16x16x32_bf16 v[2:5], v[184:187], v[216:219], v[2:5]
	v_mfma_f32_16x16x32_bf16 v[54:57], v[180:183], v[196:199], v[54:57]
	v_mfma_f32_16x16x32_bf16 v[50:53], v[188:191], v[196:199], v[50:53]
	v_mfma_f32_16x16x32_bf16 v[38:41], v[180:183], v[204:207], v[38:41]
	v_mfma_f32_16x16x32_bf16 v[34:37], v[188:191], v[204:207], v[34:37]
	v_mfma_f32_16x16x32_bf16 v[22:25], v[180:183], v[212:215], v[22:25]
	v_mfma_f32_16x16x32_bf16 v[18:21], v[188:191], v[212:215], v[18:21]
	v_mfma_f32_16x16x32_bf16 v[6:9], v[180:183], v[220:223], v[6:9]
	v_mfma_f32_16x16x32_bf16 v[2:5], v[188:191], v[220:223], v[2:5]
	s_setprio 0
	s_barrier
	s_cbranch_scc0 .LBB0_193
	s_and_b64 vcc, exec, s[16:17]
	s_cbranch_vccz .LBB0_196
	s_barrier

.LBB0_518:
	ds_read_b128 v[154:157], v150
	ds_read_b128 v[158:161], v150 offset:1024
	ds_read_b128 v[162:165], v150 offset:2048
	ds_read_b128 v[166:169], v150 offset:3072
	ds_read_b128 v[170:173], v151
	ds_read_b128 v[174:177], v151 offset:1024
	ds_read_b128 v[178:181], v151 offset:2048
	ds_read_b128 v[182:185], v151 offset:3072
	s_add_u32 s26, s24, 0xfffd0080
	s_addc_u32 s27, s25, -1
	s_cmp_eq_u32 s63, 8
	s_cselect_b32 s29, s5, s27
	s_cselect_b32 s28, s4, s26
	s_cselect_b32 s27, s23, s62
	s_cselect_b32 s26, s22, s61
	v_lshl_add_u64 v[146:147], s[24:25], 0, v[138:139]
	s_add_i32 m0, s36, 0xc000
	ds_read_b128 v[186:189], v152
	ds_read_b128 v[190:193], v152 offset:1024
	ds_read_b128 v[194:197], v152 offset:2048
	ds_read_b128 v[198:201], v152 offset:3072
	ds_read_b128 v[202:205], v152 offset:4096
	ds_read_b128 v[206:209], v152 offset:5120
	ds_read_b128 v[210:213], v152 offset:6144
	ds_read_b128 v[214:217], v152 offset:7168
	global_load_lds_dwordx4 v[146:147], off
	v_lshl_add_u64 v[146:147], s[24:25], 0, v[140:141]
	s_add_i32 m0, s36, 0xe000
	s_nop 0
	global_load_lds_dwordx4 v[146:147], off
	s_waitcnt vmcnt(8)
	s_waitcnt lgkmcnt(0)
	s_barrier
	s_setprio 1
	s_waitcnt lgkmcnt(0)
	v_mfma_f32_16x16x32_bf16 v[126:129], v[154:157], v[186:189], v[126:129]
	v_mfma_f32_16x16x32_bf16 v[122:125], v[162:165], v[186:189], v[122:125]
	v_mfma_f32_16x16x32_bf16 v[118:121], v[154:157], v[194:197], v[118:121]
	v_mfma_f32_16x16x32_bf16 v[110:113], v[162:165], v[194:197], v[110:113]
	v_mfma_f32_16x16x32_bf16 v[102:105], v[154:157], v[202:205], v[102:105]
	v_mfma_f32_16x16x32_bf16 v[94:97], v[162:165], v[202:205], v[94:97]
	v_mfma_f32_16x16x32_bf16 v[86:89], v[154:157], v[210:213], v[86:89]
	v_mfma_f32_16x16x32_bf16 v[78:81], v[162:165], v[210:213], v[78:81]
	v_mfma_f32_16x16x32_bf16 v[126:129], v[158:161], v[190:193], v[126:129]
	v_mfma_f32_16x16x32_bf16 v[122:125], v[166:169], v[190:193], v[122:125]
	v_mfma_f32_16x16x32_bf16 v[118:121], v[158:161], v[198:201], v[118:121]
	v_mfma_f32_16x16x32_bf16 v[110:113], v[166:169], v[198:201], v[110:113]
	v_mfma_f32_16x16x32_bf16 v[102:105], v[158:161], v[206:209], v[102:105]
	v_mfma_f32_16x16x32_bf16 v[94:97], v[166:169], v[206:209], v[94:97]
	v_mfma_f32_16x16x32_bf16 v[86:89], v[158:161], v[214:217], v[86:89]
	v_mfma_f32_16x16x32_bf16 v[78:81], v[166:169], v[214:217], v[78:81]
	s_setprio 0
	s_setprio 1
	v_mfma_f32_16x16x32_bf16 v[114:117], v[170:173], v[186:189], v[114:117]
	v_mfma_f32_16x16x32_bf16 v[106:109], v[178:181], v[186:189], v[106:109]
	v_mfma_f32_16x16x32_bf16 v[98:101], v[170:173], v[194:197], v[98:101]
	v_mfma_f32_16x16x32_bf16 v[90:93], v[178:181], v[194:197], v[90:93]
	v_mfma_f32_16x16x32_bf16 v[82:85], v[170:173], v[202:205], v[82:85]
	v_mfma_f32_16x16x32_bf16 v[74:77], v[178:181], v[202:205], v[74:77]
	v_mfma_f32_16x16x32_bf16 v[70:73], v[170:173], v[210:213], v[70:73]
	v_mfma_f32_16x16x32_bf16 v[66:69], v[178:181], v[210:213], v[66:69]
	v_mfma_f32_16x16x32_bf16 v[114:117], v[174:177], v[190:193], v[114:117]
	v_mfma_f32_16x16x32_bf16 v[106:109], v[182:185], v[190:193], v[106:109]
	v_mfma_f32_16x16x32_bf16 v[98:101], v[174:177], v[198:201], v[98:101]
	v_mfma_f32_16x16x32_bf16 v[90:93], v[182:185], v[198:201], v[90:93]
	v_mfma_f32_16x16x32_bf16 v[82:85], v[174:177], v[206:209], v[82:85]
	v_mfma_f32_16x16x32_bf16 v[74:77], v[182:185], v[206:209], v[74:77]
	v_mfma_f32_16x16x32_bf16 v[70:73], v[174:177], v[214:217], v[70:73]
	v_mfma_f32_16x16x32_bf16 v[66:69], v[182:185], v[214:217], v[66:69]
	s_setprio 0
	s_barrier
	s_add_i32 s64, s47, s35
	v_lshl_add_u64 v[146:147], s[26:27], 0, v[132:133]
	s_mov_b32 m0, s64
	ds_read_b128 v[186:189], v152 offset:16384
	ds_read_b128 v[190:193], v152 offset:17408
	ds_read_b128 v[194:197], v152 offset:18432
	ds_read_b128 v[198:201], v152 offset:19456
	ds_read_b128 v[202:205], v152 offset:20480
	ds_read_b128 v[206:209], v152 offset:21504
	ds_read_b128 v[210:213], v152 offset:22528
	ds_read_b128 v[214:217], v152 offset:23552
	global_load_lds_dwordx4 v[146:147], off
	s_add_i32 m0, s64, 0x2000
	s_add_u32 s64, s26, 0x30000
	v_lshl_add_u64 v[218:219], s[26:27], 0, v[136:137]
	s_addc_u32 s65, s27, 0
	s_add_i32 s66, s52, s35
	global_load_lds_dwordx4 v[218:219], off
	v_lshl_add_u64 v[220:221], s[64:65], 0, v[132:133]
	s_mov_b32 m0, s66
	v_lshl_add_u64 v[222:223], s[28:29], 0, v[134:135]
	global_load_lds_dwordx4 v[220:221], off
	v_lshl_add_u64 v[220:221], s[64:65], 0, v[136:137]
	s_add_i32 m0, s66, 0x2000
	s_nop 0
	global_load_lds_dwordx4 v[220:221], off
	v_lshl_add_u64 v[220:221], s[28:29], 0, v[130:131]
	s_mov_b32 m0, s36
	s_nop 0
	global_load_lds_dwordx4 v[220:221], off
	s_mov_b32 m0, s37
	s_nop 0
	global_load_lds_dwordx4 v[222:223], off
	s_waitcnt vmcnt(8)
	s_waitcnt lgkmcnt(0)
	s_barrier
	s_setprio 1
	s_waitcnt lgkmcnt(0)
	v_mfma_f32_16x16x32_bf16 v[62:65], v[154:157], v[186:189], v[62:65]
	v_mfma_f32_16x16x32_bf16 v[58:61], v[162:165], v[186:189], v[58:61]
	v_mfma_f32_16x16x32_bf16 v[54:57], v[154:157], v[194:197], v[54:57]
	v_mfma_f32_16x16x32_bf16 v[46:49], v[162:165], v[194:197], v[46:49]
	v_mfma_f32_16x16x32_bf16 v[38:41], v[154:157], v[202:205], v[38:41]
	v_mfma_f32_16x16x32_bf16 v[30:33], v[162:165], v[202:205], v[30:33]
	v_mfma_f32_16x16x32_bf16 v[22:25], v[154:157], v[210:213], v[22:25]
	v_mfma_f32_16x16x32_bf16 v[14:17], v[162:165], v[210:213], v[14:17]
	v_mfma_f32_16x16x32_bf16 v[62:65], v[158:161], v[190:193], v[62:65]
	v_mfma_f32_16x16x32_bf16 v[58:61], v[166:169], v[190:193], v[58:61]
	v_mfma_f32_16x16x32_bf16 v[54:57], v[158:161], v[198:201], v[54:57]
	v_mfma_f32_16x16x32_bf16 v[46:49], v[166:169], v[198:201], v[46:49]
	v_mfma_f32_16x16x32_bf16 v[38:41], v[158:161], v[206:209], v[38:41]
	v_mfma_f32_16x16x32_bf16 v[30:33], v[166:169], v[206:209], v[30:33]
	v_mfma_f32_16x16x32_bf16 v[22:25], v[158:161], v[214:217], v[22:25]
	v_mfma_f32_16x16x32_bf16 v[14:17], v[166:169], v[214:217], v[14:17]
	s_setprio 0
	s_setprio 1
	v_mfma_f32_16x16x32_bf16 v[50:53], v[170:173], v[186:189], v[50:53]
	v_mfma_f32_16x16x32_bf16 v[42:45], v[178:181], v[186:189], v[42:45]
	v_mfma_f32_16x16x32_bf16 v[34:37], v[170:173], v[194:197], v[34:37]
	v_mfma_f32_16x16x32_bf16 v[26:29], v[178:181], v[194:197], v[26:29]
	v_mfma_f32_16x16x32_bf16 v[18:21], v[170:173], v[202:205], v[18:21]
	v_mfma_f32_16x16x32_bf16 v[10:13], v[178:181], v[202:205], v[10:13]
	v_mfma_f32_16x16x32_bf16 v[6:9], v[170:173], v[210:213], v[6:9]
	v_mfma_f32_16x16x32_bf16 v[2:5], v[178:181], v[210:213], v[2:5]
	v_mfma_f32_16x16x32_bf16 v[50:53], v[174:177], v[190:193], v[50:53]
	v_mfma_f32_16x16x32_bf16 v[42:45], v[182:185], v[190:193], v[42:45]
	v_mfma_f32_16x16x32_bf16 v[34:37], v[174:177], v[198:201], v[34:37]
	v_mfma_f32_16x16x32_bf16 v[26:29], v[182:185], v[198:201], v[26:29]
	v_mfma_f32_16x16x32_bf16 v[18:21], v[174:177], v[206:209], v[18:21]
	v_mfma_f32_16x16x32_bf16 v[10:13], v[182:185], v[206:209], v[10:13]
	v_mfma_f32_16x16x32_bf16 v[6:9], v[174:177], v[214:217], v[6:9]
	v_mfma_f32_16x16x32_bf16 v[2:5], v[182:185], v[214:217], v[2:5]
	s_setprio 0
	s_barrier
	s_add_i32 s64, 0, 0x18000
	v_add_u32_e32 v153, s64, v148
	s_add_i32 s65, 0, 0x1c000
	ds_read_b128 v[154:157], v153
	ds_read_b128 v[158:161], v153 offset:1024
	ds_read_b128 v[162:165], v153 offset:2048
	ds_read_b128 v[166:169], v153 offset:3072
	v_add_u32_e32 v153, s65, v148
	ds_read_b128 v[170:173], v153
	ds_read_b128 v[174:177], v153 offset:1024
	ds_read_b128 v[178:181], v153 offset:2048
	ds_read_b128 v[182:185], v153 offset:3072
	s_add_u32 s28, s28, 0x30000
	s_addc_u32 s29, s29, 0
	s_mov_b32 m0, s38
	v_lshl_add_u64 v[224:225], s[28:29], 0, v[130:131]
	ds_read_b128 v[186:189], v152 offset:32768
	ds_read_b128 v[190:193], v152 offset:33792
	ds_read_b128 v[194:197], v152 offset:34816
	ds_read_b128 v[198:201], v152 offset:35840
	ds_read_b128 v[202:205], v152 offset:36864
	ds_read_b128 v[206:209], v152 offset:37888
	ds_read_b128 v[210:213], v152 offset:38912
	ds_read_b128 v[214:217], v152 offset:39936
	global_load_lds_dwordx4 v[224:225], off
	v_lshl_add_u64 v[224:225], s[28:29], 0, v[134:135]
	s_mov_b32 m0, s39
	s_nop 0
	global_load_lds_dwordx4 v[224:225], off
	s_waitcnt vmcnt(8)
	s_waitcnt lgkmcnt(0)
	s_barrier
	s_setprio 1
	s_waitcnt lgkmcnt(0)
	v_mfma_f32_16x16x32_bf16 v[126:129], v[154:157], v[186:189], v[126:129]
	v_mfma_f32_16x16x32_bf16 v[122:125], v[162:165], v[186:189], v[122:125]
	v_mfma_f32_16x16x32_bf16 v[118:121], v[154:157], v[194:197], v[118:121]
	v_mfma_f32_16x16x32_bf16 v[110:113], v[162:165], v[194:197], v[110:113]
	v_mfma_f32_16x16x32_bf16 v[102:105], v[154:157], v[202:205], v[102:105]
	v_mfma_f32_16x16x32_bf16 v[94:97], v[162:165], v[202:205], v[94:97]
	v_mfma_f32_16x16x32_bf16 v[86:89], v[154:157], v[210:213], v[86:89]
	v_mfma_f32_16x16x32_bf16 v[78:81], v[162:165], v[210:213], v[78:81]
	v_mfma_f32_16x16x32_bf16 v[126:129], v[158:161], v[190:193], v[126:129]
	v_mfma_f32_16x16x32_bf16 v[122:125], v[166:169], v[190:193], v[122:125]
	v_mfma_f32_16x16x32_bf16 v[118:121], v[158:161], v[198:201], v[118:121]
	v_mfma_f32_16x16x32_bf16 v[110:113], v[166:169], v[198:201], v[110:113]
	v_mfma_f32_16x16x32_bf16 v[102:105], v[158:161], v[206:209], v[102:105]
	v_mfma_f32_16x16x32_bf16 v[94:97], v[166:169], v[206:209], v[94:97]
	v_mfma_f32_16x16x32_bf16 v[86:89], v[158:161], v[214:217], v[86:89]
	v_mfma_f32_16x16x32_bf16 v[78:81], v[166:169], v[214:217], v[78:81]
	s_setprio 0
	s_setprio 1
	v_mfma_f32_16x16x32_bf16 v[114:117], v[170:173], v[186:189], v[114:117]
	v_mfma_f32_16x16x32_bf16 v[106:109], v[178:181], v[186:189], v[106:109]
	v_mfma_f32_16x16x32_bf16 v[98:101], v[170:173], v[194:197], v[98:101]
	v_mfma_f32_16x16x32_bf16 v[90:93], v[178:181], v[194:197], v[90:93]
	v_mfma_f32_16x16x32_bf16 v[82:85], v[170:173], v[202:205], v[82:85]
	v_mfma_f32_16x16x32_bf16 v[74:77], v[178:181], v[202:205], v[74:77]
	v_mfma_f32_16x16x32_bf16 v[70:73], v[170:173], v[210:213], v[70:73]
	v_mfma_f32_16x16x32_bf16 v[66:69], v[178:181], v[210:213], v[66:69]
	v_mfma_f32_16x16x32_bf16 v[114:117], v[174:177], v[190:193], v[114:117]
	v_mfma_f32_16x16x32_bf16 v[106:109], v[182:185], v[190:193], v[106:109]
	v_mfma_f32_16x16x32_bf16 v[98:101], v[174:177], v[198:201], v[98:101]
	v_mfma_f32_16x16x32_bf16 v[90:93], v[182:185], v[198:201], v[90:93]
	v_mfma_f32_16x16x32_bf16 v[82:85], v[174:177], v[206:209], v[82:85]
	v_mfma_f32_16x16x32_bf16 v[74:77], v[182:185], v[206:209], v[74:77]
	v_mfma_f32_16x16x32_bf16 v[70:73], v[174:177], v[214:217], v[70:73]
	v_mfma_f32_16x16x32_bf16 v[66:69], v[182:185], v[214:217], v[66:69]
	s_setprio 0
	s_barrier
	s_add_i32 s28, s64, s35
	v_lshl_add_u64 v[146:147], v[146:147], 0, s[10:11]
	s_mov_b32 m0, s28
	ds_read_b128 v[186:189], v152 offset:49152
	ds_read_b128 v[190:193], v152 offset:50176
	ds_read_b128 v[194:197], v152 offset:51200
	ds_read_b128 v[198:201], v152 offset:52224
	ds_read_b128 v[202:205], v152 offset:53248
	ds_read_b128 v[206:209], v152 offset:54272
	ds_read_b128 v[210:213], v152 offset:55296
	ds_read_b128 v[214:217], v152 offset:56320
	global_load_lds_dwordx4 v[146:147], off
	s_add_i32 m0, s28, 0x2000
	s_add_u32 s26, s26, 0x30080
	v_lshl_add_u64 v[146:147], v[218:219], 0, s[10:11]
	s_addc_u32 s27, s27, 0
	s_add_i32 s28, s65, s35
	global_load_lds_dwordx4 v[146:147], off
	v_lshl_add_u64 v[146:147], s[26:27], 0, v[132:133]
	s_mov_b32 m0, s28
	s_nop 0
	global_load_lds_dwordx4 v[146:147], off
	v_lshl_add_u64 v[146:147], s[26:27], 0, v[136:137]
	s_add_i32 m0, s28, 0x2000
	s_nop 0
	global_load_lds_dwordx4 v[146:147], off
	v_lshl_add_u64 v[146:147], v[220:221], 0, s[10:11]
	s_mov_b32 m0, s41
	s_nop 0
	global_load_lds_dwordx4 v[146:147], off
	v_lshl_add_u64 v[146:147], v[222:223], 0, s[10:11]
	s_mov_b32 m0, s44
	s_nop 0
	global_load_lds_dwordx4 v[146:147], off
	s_waitcnt vmcnt(8)
	s_waitcnt lgkmcnt(0)
	s_barrier
	s_add_i32 s63, s63, 2
	s_add_u32 s24, s24, 0x100
	s_addc_u32 s25, s25, 0
	s_add_u32 s61, s61, 0x100
	s_addc_u32 s62, s62, 0
	s_cmp_gt_u32 s63, 9
	s_setprio 1
	s_waitcnt lgkmcnt(0)
	v_mfma_f32_16x16x32_bf16 v[62:65], v[154:157], v[186:189], v[62:65]
	v_mfma_f32_16x16x32_bf16 v[58:61], v[162:165], v[186:189], v[58:61]
	v_mfma_f32_16x16x32_bf16 v[54:57], v[154:157], v[194:197], v[54:57]
	v_mfma_f32_16x16x32_bf16 v[46:49], v[162:165], v[194:197], v[46:49]
	v_mfma_f32_16x16x32_bf16 v[38:41], v[154:157], v[202:205], v[38:41]
	v_mfma_f32_16x16x32_bf16 v[30:33], v[162:165], v[202:205], v[30:33]
	v_mfma_f32_16x16x32_bf16 v[22:25], v[154:157], v[210:213], v[22:25]
	v_mfma_f32_16x16x32_bf16 v[14:17], v[162:165], v[210:213], v[14:17]
	v_mfma_f32_16x16x32_bf16 v[62:65], v[158:161], v[190:193], v[62:65]
	v_mfma_f32_16x16x32_bf16 v[58:61], v[166:169], v[190:193], v[58:61]
	v_mfma_f32_16x16x32_bf16 v[54:57], v[158:161], v[198:201], v[54:57]
	v_mfma_f32_16x16x32_bf16 v[46:49], v[166:169], v[198:201], v[46:49]
	v_mfma_f32_16x16x32_bf16 v[38:41], v[158:161], v[206:209], v[38:41]
	v_mfma_f32_16x16x32_bf16 v[30:33], v[166:169], v[206:209], v[30:33]
	v_mfma_f32_16x16x32_bf16 v[22:25], v[158:161], v[214:217], v[22:25]
	v_mfma_f32_16x16x32_bf16 v[14:17], v[166:169], v[214:217], v[14:17]
	s_setprio 0
	s_setprio 1
	v_mfma_f32_16x16x32_bf16 v[50:53], v[170:173], v[186:189], v[50:53]
	v_mfma_f32_16x16x32_bf16 v[42:45], v[178:181], v[186:189], v[42:45]
	v_mfma_f32_16x16x32_bf16 v[34:37], v[170:173], v[194:197], v[34:37]
	v_mfma_f32_16x16x32_bf16 v[26:29], v[178:181], v[194:197], v[26:29]
	v_mfma_f32_16x16x32_bf16 v[18:21], v[170:173], v[202:205], v[18:21]
	v_mfma_f32_16x16x32_bf16 v[10:13], v[178:181], v[202:205], v[10:13]
	v_mfma_f32_16x16x32_bf16 v[6:9], v[170:173], v[210:213], v[6:9]
	v_mfma_f32_16x16x32_bf16 v[2:5], v[178:181], v[210:213], v[2:5]
	v_mfma_f32_16x16x32_bf16 v[50:53], v[174:177], v[190:193], v[50:53]
	v_mfma_f32_16x16x32_bf16 v[42:45], v[182:185], v[190:193], v[42:45]
	v_mfma_f32_16x16x32_bf16 v[34:37], v[174:177], v[198:201], v[34:37]
	v_mfma_f32_16x16x32_bf16 v[26:29], v[182:185], v[198:201], v[26:29]
	v_mfma_f32_16x16x32_bf16 v[18:21], v[174:177], v[206:209], v[18:21]
	v_mfma_f32_16x16x32_bf16 v[10:13], v[182:185], v[206:209], v[10:13]
	v_mfma_f32_16x16x32_bf16 v[6:9], v[174:177], v[214:217], v[6:9]
	v_mfma_f32_16x16x32_bf16 v[2:5], v[182:185], v[214:217], v[2:5]
	s_setprio 0
	s_barrier
	s_cbranch_scc0 .LBB0_518
	s_and_b64 vcc, exec, s[12:13]
	s_cbranch_vccz .LBB0_521
	s_barrier

.LBB0_653:
	ds_read_b128 v[154:157], v150
	ds_read_b128 v[158:161], v150 offset:1024
	ds_read_b128 v[162:165], v150 offset:2048
	ds_read_b128 v[166:169], v150 offset:3072
	ds_read_b128 v[170:173], v151
	ds_read_b128 v[174:177], v151 offset:1024
	ds_read_b128 v[178:181], v151 offset:2048
	ds_read_b128 v[182:185], v151 offset:3072
	s_add_u32 s34, s30, 0xfffc0080
	s_addc_u32 s35, s31, -1
	s_cmp_eq_u32 s67, 12
	s_cselect_b32 s37, s23, s35
	s_cselect_b32 s36, s63, s34
	s_cselect_b32 s35, s21, s66
	s_cselect_b32 s34, s64, s65
	v_lshl_add_u64 v[146:147], s[30:31], 0, v[138:139]
	s_add_i32 m0, s29, 0xc000
	ds_read_b128 v[186:189], v152
	ds_read_b128 v[190:193], v152 offset:1024
	ds_read_b128 v[194:197], v152 offset:2048
	ds_read_b128 v[198:201], v152 offset:3072
	ds_read_b128 v[202:205], v152 offset:4096
	ds_read_b128 v[206:209], v152 offset:5120
	ds_read_b128 v[210:213], v152 offset:6144
	ds_read_b128 v[214:217], v152 offset:7168
	global_load_lds_dwordx4 v[146:147], off
	v_lshl_add_u64 v[146:147], s[30:31], 0, v[140:141]
	s_add_i32 m0, s29, 0xe000
	s_nop 0
	global_load_lds_dwordx4 v[146:147], off
	s_waitcnt vmcnt(8)
	s_waitcnt lgkmcnt(0)
	s_barrier
	s_setprio 1
	s_waitcnt lgkmcnt(0)
	v_mfma_f32_16x16x32_bf16 v[126:129], v[154:157], v[186:189], v[126:129]
	v_mfma_f32_16x16x32_bf16 v[122:125], v[162:165], v[186:189], v[122:125]
	v_mfma_f32_16x16x32_bf16 v[110:113], v[154:157], v[194:197], v[110:113]
	v_mfma_f32_16x16x32_bf16 v[106:109], v[162:165], v[194:197], v[106:109]
	v_mfma_f32_16x16x32_bf16 v[94:97], v[154:157], v[202:205], v[94:97]
	v_mfma_f32_16x16x32_bf16 v[90:93], v[162:165], v[202:205], v[90:93]
	v_mfma_f32_16x16x32_bf16 v[78:81], v[154:157], v[210:213], v[78:81]
	v_mfma_f32_16x16x32_bf16 v[74:77], v[162:165], v[210:213], v[74:77]
	v_mfma_f32_16x16x32_bf16 v[126:129], v[158:161], v[190:193], v[126:129]
	v_mfma_f32_16x16x32_bf16 v[122:125], v[166:169], v[190:193], v[122:125]
	v_mfma_f32_16x16x32_bf16 v[110:113], v[158:161], v[198:201], v[110:113]
	v_mfma_f32_16x16x32_bf16 v[106:109], v[166:169], v[198:201], v[106:109]
	v_mfma_f32_16x16x32_bf16 v[94:97], v[158:161], v[206:209], v[94:97]
	v_mfma_f32_16x16x32_bf16 v[90:93], v[166:169], v[206:209], v[90:93]
	v_mfma_f32_16x16x32_bf16 v[78:81], v[158:161], v[214:217], v[78:81]
	v_mfma_f32_16x16x32_bf16 v[74:77], v[166:169], v[214:217], v[74:77]
	s_setprio 0
	s_setprio 1
	v_mfma_f32_16x16x32_bf16 v[118:121], v[170:173], v[186:189], v[118:121]
	v_mfma_f32_16x16x32_bf16 v[114:117], v[178:181], v[186:189], v[114:117]
	v_mfma_f32_16x16x32_bf16 v[102:105], v[170:173], v[194:197], v[102:105]
	v_mfma_f32_16x16x32_bf16 v[98:101], v[178:181], v[194:197], v[98:101]
	v_mfma_f32_16x16x32_bf16 v[86:89], v[170:173], v[202:205], v[86:89]
	v_mfma_f32_16x16x32_bf16 v[82:85], v[178:181], v[202:205], v[82:85]
	v_mfma_f32_16x16x32_bf16 v[70:73], v[170:173], v[210:213], v[70:73]
	v_mfma_f32_16x16x32_bf16 v[66:69], v[178:181], v[210:213], v[66:69]
	v_mfma_f32_16x16x32_bf16 v[118:121], v[174:177], v[190:193], v[118:121]
	v_mfma_f32_16x16x32_bf16 v[114:117], v[182:185], v[190:193], v[114:117]
	v_mfma_f32_16x16x32_bf16 v[102:105], v[174:177], v[198:201], v[102:105]
	v_mfma_f32_16x16x32_bf16 v[98:101], v[182:185], v[198:201], v[98:101]
	v_mfma_f32_16x16x32_bf16 v[86:89], v[174:177], v[206:209], v[86:89]
	v_mfma_f32_16x16x32_bf16 v[82:85], v[182:185], v[206:209], v[82:85]
	v_mfma_f32_16x16x32_bf16 v[70:73], v[174:177], v[214:217], v[70:73]
	v_mfma_f32_16x16x32_bf16 v[66:69], v[182:185], v[214:217], v[66:69]
	s_setprio 0
	s_barrier
	s_add_i32 s68, s56, s41
	v_lshl_add_u64 v[146:147], s[34:35], 0, v[132:133]
	s_mov_b32 m0, s68
	ds_read_b128 v[186:189], v152 offset:16384
	ds_read_b128 v[190:193], v152 offset:17408
	ds_read_b128 v[194:197], v152 offset:18432
	ds_read_b128 v[198:201], v152 offset:19456
	ds_read_b128 v[202:205], v152 offset:20480
	ds_read_b128 v[206:209], v152 offset:21504
	ds_read_b128 v[210:213], v152 offset:22528
	ds_read_b128 v[214:217], v152 offset:23552
	global_load_lds_dwordx4 v[146:147], off
	s_add_i32 m0, s68, 0x2000
	s_add_u32 s68, s34, 0x40000
	v_lshl_add_u64 v[218:219], s[34:35], 0, v[136:137]
	s_addc_u32 s69, s35, 0
	s_add_i32 s70, s57, s41
	global_load_lds_dwordx4 v[218:219], off
	v_lshl_add_u64 v[220:221], s[68:69], 0, v[132:133]
	s_mov_b32 m0, s70
	v_lshl_add_u64 v[222:223], s[36:37], 0, v[134:135]
	global_load_lds_dwordx4 v[220:221], off
	v_lshl_add_u64 v[220:221], s[68:69], 0, v[136:137]
	s_add_i32 m0, s70, 0x2000
	s_nop 0
	global_load_lds_dwordx4 v[220:221], off
	v_lshl_add_u64 v[220:221], s[36:37], 0, v[130:131]
	s_mov_b32 m0, s29
	s_nop 0
	global_load_lds_dwordx4 v[220:221], off
	s_mov_b32 m0, s44
	s_nop 0
	global_load_lds_dwordx4 v[222:223], off
	s_waitcnt vmcnt(8)
	s_waitcnt lgkmcnt(0)
	s_barrier
	s_setprio 1
	s_waitcnt lgkmcnt(0)
	v_mfma_f32_16x16x32_bf16 v[62:65], v[154:157], v[186:189], v[62:65]
	v_mfma_f32_16x16x32_bf16 v[58:61], v[162:165], v[186:189], v[58:61]
	v_mfma_f32_16x16x32_bf16 v[46:49], v[154:157], v[194:197], v[46:49]
	v_mfma_f32_16x16x32_bf16 v[42:45], v[162:165], v[194:197], v[42:45]
	v_mfma_f32_16x16x32_bf16 v[30:33], v[154:157], v[202:205], v[30:33]
	v_mfma_f32_16x16x32_bf16 v[26:29], v[162:165], v[202:205], v[26:29]
	v_mfma_f32_16x16x32_bf16 v[14:17], v[154:157], v[210:213], v[14:17]
	v_mfma_f32_16x16x32_bf16 v[10:13], v[162:165], v[210:213], v[10:13]
	v_mfma_f32_16x16x32_bf16 v[62:65], v[158:161], v[190:193], v[62:65]
	v_mfma_f32_16x16x32_bf16 v[58:61], v[166:169], v[190:193], v[58:61]
	v_mfma_f32_16x16x32_bf16 v[46:49], v[158:161], v[198:201], v[46:49]
	v_mfma_f32_16x16x32_bf16 v[42:45], v[166:169], v[198:201], v[42:45]
	v_mfma_f32_16x16x32_bf16 v[30:33], v[158:161], v[206:209], v[30:33]
	v_mfma_f32_16x16x32_bf16 v[26:29], v[166:169], v[206:209], v[26:29]
	v_mfma_f32_16x16x32_bf16 v[14:17], v[158:161], v[214:217], v[14:17]
	v_mfma_f32_16x16x32_bf16 v[10:13], v[166:169], v[214:217], v[10:13]
	s_setprio 0
	s_setprio 1
	v_mfma_f32_16x16x32_bf16 v[54:57], v[170:173], v[186:189], v[54:57]
	v_mfma_f32_16x16x32_bf16 v[50:53], v[178:181], v[186:189], v[50:53]
	v_mfma_f32_16x16x32_bf16 v[38:41], v[170:173], v[194:197], v[38:41]
	v_mfma_f32_16x16x32_bf16 v[34:37], v[178:181], v[194:197], v[34:37]
	v_mfma_f32_16x16x32_bf16 v[22:25], v[170:173], v[202:205], v[22:25]
	v_mfma_f32_16x16x32_bf16 v[18:21], v[178:181], v[202:205], v[18:21]
	v_mfma_f32_16x16x32_bf16 v[6:9], v[170:173], v[210:213], v[6:9]
	v_mfma_f32_16x16x32_bf16 v[2:5], v[178:181], v[210:213], v[2:5]
	v_mfma_f32_16x16x32_bf16 v[54:57], v[174:177], v[190:193], v[54:57]
	v_mfma_f32_16x16x32_bf16 v[50:53], v[182:185], v[190:193], v[50:53]
	v_mfma_f32_16x16x32_bf16 v[38:41], v[174:177], v[198:201], v[38:41]
	v_mfma_f32_16x16x32_bf16 v[34:37], v[182:185], v[198:201], v[34:37]
	v_mfma_f32_16x16x32_bf16 v[22:25], v[174:177], v[206:209], v[22:25]
	v_mfma_f32_16x16x32_bf16 v[18:21], v[182:185], v[206:209], v[18:21]
	v_mfma_f32_16x16x32_bf16 v[6:9], v[174:177], v[214:217], v[6:9]
	v_mfma_f32_16x16x32_bf16 v[2:5], v[182:185], v[214:217], v[2:5]
	s_setprio 0
	s_barrier
	s_add_i32 s68, 0, 0x18000
	v_add_u32_e32 v153, s68, v148
	s_add_i32 s69, 0, 0x1c000
	ds_read_b128 v[154:157], v153
	ds_read_b128 v[158:161], v153 offset:1024
	ds_read_b128 v[162:165], v153 offset:2048
	ds_read_b128 v[166:169], v153 offset:3072
	v_add_u32_e32 v153, s69, v148
	ds_read_b128 v[170:173], v153
	ds_read_b128 v[174:177], v153 offset:1024
	ds_read_b128 v[178:181], v153 offset:2048
	ds_read_b128 v[182:185], v153 offset:3072
	s_add_u32 s36, s36, 0x40000
	s_addc_u32 s37, s37, 0
	s_mov_b32 m0, s45
	v_lshl_add_u64 v[224:225], s[36:37], 0, v[130:131]
	ds_read_b128 v[186:189], v152 offset:32768
	ds_read_b128 v[190:193], v152 offset:33792
	ds_read_b128 v[194:197], v152 offset:34816
	ds_read_b128 v[198:201], v152 offset:35840
	ds_read_b128 v[202:205], v152 offset:36864
	ds_read_b128 v[206:209], v152 offset:37888
	ds_read_b128 v[210:213], v152 offset:38912
	ds_read_b128 v[214:217], v152 offset:39936
	global_load_lds_dwordx4 v[224:225], off
	v_lshl_add_u64 v[224:225], s[36:37], 0, v[134:135]
	s_mov_b32 m0, s46
	s_nop 0
	global_load_lds_dwordx4 v[224:225], off
	s_waitcnt vmcnt(8)
	s_waitcnt lgkmcnt(0)
	s_barrier
	s_setprio 1
	s_waitcnt lgkmcnt(0)
	v_mfma_f32_16x16x32_bf16 v[126:129], v[154:157], v[186:189], v[126:129]
	v_mfma_f32_16x16x32_bf16 v[122:125], v[162:165], v[186:189], v[122:125]
	v_mfma_f32_16x16x32_bf16 v[110:113], v[154:157], v[194:197], v[110:113]
	v_mfma_f32_16x16x32_bf16 v[106:109], v[162:165], v[194:197], v[106:109]
	v_mfma_f32_16x16x32_bf16 v[94:97], v[154:157], v[202:205], v[94:97]
	v_mfma_f32_16x16x32_bf16 v[90:93], v[162:165], v[202:205], v[90:93]
	v_mfma_f32_16x16x32_bf16 v[78:81], v[154:157], v[210:213], v[78:81]
	v_mfma_f32_16x16x32_bf16 v[74:77], v[162:165], v[210:213], v[74:77]
	v_mfma_f32_16x16x32_bf16 v[126:129], v[158:161], v[190:193], v[126:129]
	v_mfma_f32_16x16x32_bf16 v[122:125], v[166:169], v[190:193], v[122:125]
	v_mfma_f32_16x16x32_bf16 v[110:113], v[158:161], v[198:201], v[110:113]
	v_mfma_f32_16x16x32_bf16 v[106:109], v[166:169], v[198:201], v[106:109]
	v_mfma_f32_16x16x32_bf16 v[94:97], v[158:161], v[206:209], v[94:97]
	v_mfma_f32_16x16x32_bf16 v[90:93], v[166:169], v[206:209], v[90:93]
	v_mfma_f32_16x16x32_bf16 v[78:81], v[158:161], v[214:217], v[78:81]
	v_mfma_f32_16x16x32_bf16 v[74:77], v[166:169], v[214:217], v[74:77]
	s_setprio 0
	s_setprio 1
	v_mfma_f32_16x16x32_bf16 v[118:121], v[170:173], v[186:189], v[118:121]
	v_mfma_f32_16x16x32_bf16 v[114:117], v[178:181], v[186:189], v[114:117]
	v_mfma_f32_16x16x32_bf16 v[102:105], v[170:173], v[194:197], v[102:105]
	v_mfma_f32_16x16x32_bf16 v[98:101], v[178:181], v[194:197], v[98:101]
	v_mfma_f32_16x16x32_bf16 v[86:89], v[170:173], v[202:205], v[86:89]
	v_mfma_f32_16x16x32_bf16 v[82:85], v[178:181], v[202:205], v[82:85]
	v_mfma_f32_16x16x32_bf16 v[70:73], v[170:173], v[210:213], v[70:73]
	v_mfma_f32_16x16x32_bf16 v[66:69], v[178:181], v[210:213], v[66:69]
	v_mfma_f32_16x16x32_bf16 v[118:121], v[174:177], v[190:193], v[118:121]
	v_mfma_f32_16x16x32_bf16 v[114:117], v[182:185], v[190:193], v[114:117]
	v_mfma_f32_16x16x32_bf16 v[102:105], v[174:177], v[198:201], v[102:105]
	v_mfma_f32_16x16x32_bf16 v[98:101], v[182:185], v[198:201], v[98:101]
	v_mfma_f32_16x16x32_bf16 v[86:89], v[174:177], v[206:209], v[86:89]
	v_mfma_f32_16x16x32_bf16 v[82:85], v[182:185], v[206:209], v[82:85]
	v_mfma_f32_16x16x32_bf16 v[70:73], v[174:177], v[214:217], v[70:73]
	v_mfma_f32_16x16x32_bf16 v[66:69], v[182:185], v[214:217], v[66:69]
	s_setprio 0
	s_barrier
	s_add_i32 s36, s68, s41
	v_lshl_add_u64 v[146:147], v[146:147], 0, s[8:9]
	s_mov_b32 m0, s36
	ds_read_b128 v[186:189], v152 offset:49152
	ds_read_b128 v[190:193], v152 offset:50176
	ds_read_b128 v[194:197], v152 offset:51200
	ds_read_b128 v[198:201], v152 offset:52224
	ds_read_b128 v[202:205], v152 offset:53248
	ds_read_b128 v[206:209], v152 offset:54272
	ds_read_b128 v[210:213], v152 offset:55296
	ds_read_b128 v[214:217], v152 offset:56320
	global_load_lds_dwordx4 v[146:147], off
	s_add_i32 m0, s36, 0x2000
	s_add_u32 s34, s34, 0x40080
	v_lshl_add_u64 v[146:147], v[218:219], 0, s[8:9]
	s_addc_u32 s35, s35, 0
	s_add_i32 s36, s69, s41
	global_load_lds_dwordx4 v[146:147], off
	v_lshl_add_u64 v[146:147], s[34:35], 0, v[132:133]
	s_mov_b32 m0, s36
	s_nop 0
	global_load_lds_dwordx4 v[146:147], off
	v_lshl_add_u64 v[146:147], s[34:35], 0, v[136:137]
	s_add_i32 m0, s36, 0x2000
	s_nop 0
	global_load_lds_dwordx4 v[146:147], off
	v_lshl_add_u64 v[146:147], v[220:221], 0, s[8:9]
	s_mov_b32 m0, s52
	s_nop 0
	global_load_lds_dwordx4 v[146:147], off
	v_lshl_add_u64 v[146:147], v[222:223], 0, s[8:9]
	s_mov_b32 m0, s53
	s_nop 0
	global_load_lds_dwordx4 v[146:147], off
	s_waitcnt vmcnt(8)
	s_waitcnt lgkmcnt(0)
	s_barrier
	s_add_i32 s67, s67, 2
	s_add_u32 s30, s30, 0x100
	s_addc_u32 s31, s31, 0
	s_add_u32 s65, s65, 0x100
	s_addc_u32 s66, s66, 0
	s_cmp_gt_u32 s67, 13
	s_setprio 1
	s_waitcnt lgkmcnt(0)
	v_mfma_f32_16x16x32_bf16 v[62:65], v[154:157], v[186:189], v[62:65]
	v_mfma_f32_16x16x32_bf16 v[58:61], v[162:165], v[186:189], v[58:61]
	v_mfma_f32_16x16x32_bf16 v[46:49], v[154:157], v[194:197], v[46:49]
	v_mfma_f32_16x16x32_bf16 v[42:45], v[162:165], v[194:197], v[42:45]
	v_mfma_f32_16x16x32_bf16 v[30:33], v[154:157], v[202:205], v[30:33]
	v_mfma_f32_16x16x32_bf16 v[26:29], v[162:165], v[202:205], v[26:29]
	v_mfma_f32_16x16x32_bf16 v[14:17], v[154:157], v[210:213], v[14:17]
	v_mfma_f32_16x16x32_bf16 v[10:13], v[162:165], v[210:213], v[10:13]
	v_mfma_f32_16x16x32_bf16 v[62:65], v[158:161], v[190:193], v[62:65]
	v_mfma_f32_16x16x32_bf16 v[58:61], v[166:169], v[190:193], v[58:61]
	v_mfma_f32_16x16x32_bf16 v[46:49], v[158:161], v[198:201], v[46:49]
	v_mfma_f32_16x16x32_bf16 v[42:45], v[166:169], v[198:201], v[42:45]
	v_mfma_f32_16x16x32_bf16 v[30:33], v[158:161], v[206:209], v[30:33]
	v_mfma_f32_16x16x32_bf16 v[26:29], v[166:169], v[206:209], v[26:29]
	v_mfma_f32_16x16x32_bf16 v[14:17], v[158:161], v[214:217], v[14:17]
	v_mfma_f32_16x16x32_bf16 v[10:13], v[166:169], v[214:217], v[10:13]
	s_setprio 0
	s_setprio 1
	v_mfma_f32_16x16x32_bf16 v[54:57], v[170:173], v[186:189], v[54:57]
	v_mfma_f32_16x16x32_bf16 v[50:53], v[178:181], v[186:189], v[50:53]
	v_mfma_f32_16x16x32_bf16 v[38:41], v[170:173], v[194:197], v[38:41]
	v_mfma_f32_16x16x32_bf16 v[34:37], v[178:181], v[194:197], v[34:37]
	v_mfma_f32_16x16x32_bf16 v[22:25], v[170:173], v[202:205], v[22:25]
	v_mfma_f32_16x16x32_bf16 v[18:21], v[178:181], v[202:205], v[18:21]
	v_mfma_f32_16x16x32_bf16 v[6:9], v[170:173], v[210:213], v[6:9]
	v_mfma_f32_16x16x32_bf16 v[2:5], v[178:181], v[210:213], v[2:5]
	v_mfma_f32_16x16x32_bf16 v[54:57], v[174:177], v[190:193], v[54:57]
	v_mfma_f32_16x16x32_bf16 v[50:53], v[182:185], v[190:193], v[50:53]
	v_mfma_f32_16x16x32_bf16 v[38:41], v[174:177], v[198:201], v[38:41]
	v_mfma_f32_16x16x32_bf16 v[34:37], v[182:185], v[198:201], v[34:37]
	v_mfma_f32_16x16x32_bf16 v[22:25], v[174:177], v[206:209], v[22:25]
	v_mfma_f32_16x16x32_bf16 v[18:21], v[182:185], v[206:209], v[18:21]
	v_mfma_f32_16x16x32_bf16 v[6:9], v[174:177], v[214:217], v[6:9]
	v_mfma_f32_16x16x32_bf16 v[2:5], v[182:185], v[214:217], v[2:5]
	s_setprio 0
	s_barrier
	s_cbranch_scc0 .LBB0_653
	s_and_b64 vcc, exec, s[10:11]
	s_cbranch_vccz .LBB0_656
	s_barrier

.LBB0_728:
	ds_read_b128 v[154:157], v150
	ds_read_b128 v[158:161], v150 offset:1024
	ds_read_b128 v[162:165], v150 offset:2048
	ds_read_b128 v[166:169], v150 offset:3072
	ds_read_b128 v[170:173], v151
	ds_read_b128 v[174:177], v151 offset:1024
	ds_read_b128 v[178:181], v151 offset:2048
	ds_read_b128 v[182:185], v151 offset:3072
	s_add_u32 s34, s30, 0xfff00080
	s_addc_u32 s35, s31, -1
	s_cmp_eq_u32 s67, 60
	s_cselect_b32 s37, s23, s35
	s_cselect_b32 s36, s63, s34
	s_cselect_b32 s35, s21, s66
	s_cselect_b32 s34, s64, s65
	v_lshl_add_u64 v[146:147], s[30:31], 0, v[138:139]
	s_add_i32 m0, s29, 0xc000
	ds_read_b128 v[186:189], v152
	ds_read_b128 v[190:193], v152 offset:1024
	ds_read_b128 v[194:197], v152 offset:2048
	ds_read_b128 v[198:201], v152 offset:3072
	ds_read_b128 v[202:205], v152 offset:4096
	ds_read_b128 v[206:209], v152 offset:5120
	ds_read_b128 v[210:213], v152 offset:6144
	ds_read_b128 v[214:217], v152 offset:7168
	global_load_lds_dwordx4 v[146:147], off
	v_lshl_add_u64 v[146:147], s[30:31], 0, v[140:141]
	s_add_i32 m0, s29, 0xe000
	s_nop 0
	global_load_lds_dwordx4 v[146:147], off
	s_waitcnt vmcnt(8)
	s_waitcnt lgkmcnt(0)
	s_barrier
	s_setprio 1
	s_waitcnt lgkmcnt(0)
	v_mfma_f32_16x16x32_bf16 v[126:129], v[154:157], v[186:189], v[126:129]
	v_mfma_f32_16x16x32_bf16 v[122:125], v[162:165], v[186:189], v[122:125]
	v_mfma_f32_16x16x32_bf16 v[118:121], v[154:157], v[194:197], v[118:121]
	v_mfma_f32_16x16x32_bf16 v[110:113], v[162:165], v[194:197], v[110:113]
	v_mfma_f32_16x16x32_bf16 v[102:105], v[154:157], v[202:205], v[102:105]
	v_mfma_f32_16x16x32_bf16 v[94:97], v[162:165], v[202:205], v[94:97]
	v_mfma_f32_16x16x32_bf16 v[86:89], v[154:157], v[210:213], v[86:89]
	v_mfma_f32_16x16x32_bf16 v[78:81], v[162:165], v[210:213], v[78:81]
	v_mfma_f32_16x16x32_bf16 v[126:129], v[158:161], v[190:193], v[126:129]
	v_mfma_f32_16x16x32_bf16 v[122:125], v[166:169], v[190:193], v[122:125]
	v_mfma_f32_16x16x32_bf16 v[118:121], v[158:161], v[198:201], v[118:121]
	v_mfma_f32_16x16x32_bf16 v[110:113], v[166:169], v[198:201], v[110:113]
	v_mfma_f32_16x16x32_bf16 v[102:105], v[158:161], v[206:209], v[102:105]
	v_mfma_f32_16x16x32_bf16 v[94:97], v[166:169], v[206:209], v[94:97]
	v_mfma_f32_16x16x32_bf16 v[86:89], v[158:161], v[214:217], v[86:89]
	v_mfma_f32_16x16x32_bf16 v[78:81], v[166:169], v[214:217], v[78:81]
	s_setprio 0
	s_setprio 1
	v_mfma_f32_16x16x32_bf16 v[114:117], v[170:173], v[186:189], v[114:117]
	v_mfma_f32_16x16x32_bf16 v[106:109], v[178:181], v[186:189], v[106:109]
	v_mfma_f32_16x16x32_bf16 v[98:101], v[170:173], v[194:197], v[98:101]
	v_mfma_f32_16x16x32_bf16 v[90:93], v[178:181], v[194:197], v[90:93]
	v_mfma_f32_16x16x32_bf16 v[82:85], v[170:173], v[202:205], v[82:85]
	v_mfma_f32_16x16x32_bf16 v[74:77], v[178:181], v[202:205], v[74:77]
	v_mfma_f32_16x16x32_bf16 v[70:73], v[170:173], v[210:213], v[70:73]
	v_mfma_f32_16x16x32_bf16 v[66:69], v[178:181], v[210:213], v[66:69]
	v_mfma_f32_16x16x32_bf16 v[114:117], v[174:177], v[190:193], v[114:117]
	v_mfma_f32_16x16x32_bf16 v[106:109], v[182:185], v[190:193], v[106:109]
	v_mfma_f32_16x16x32_bf16 v[98:101], v[174:177], v[198:201], v[98:101]
	v_mfma_f32_16x16x32_bf16 v[90:93], v[182:185], v[198:201], v[90:93]
	v_mfma_f32_16x16x32_bf16 v[82:85], v[174:177], v[206:209], v[82:85]
	v_mfma_f32_16x16x32_bf16 v[74:77], v[182:185], v[206:209], v[74:77]
	v_mfma_f32_16x16x32_bf16 v[70:73], v[174:177], v[214:217], v[70:73]
	v_mfma_f32_16x16x32_bf16 v[66:69], v[182:185], v[214:217], v[66:69]
	s_setprio 0
	s_barrier
	s_add_i32 s68, s56, s41
	v_lshl_add_u64 v[146:147], s[34:35], 0, v[132:133]
	s_mov_b32 m0, s68
	ds_read_b128 v[186:189], v152 offset:16384
	ds_read_b128 v[190:193], v152 offset:17408
	ds_read_b128 v[194:197], v152 offset:18432
	ds_read_b128 v[198:201], v152 offset:19456
	ds_read_b128 v[202:205], v152 offset:20480
	ds_read_b128 v[206:209], v152 offset:21504
	ds_read_b128 v[210:213], v152 offset:22528
	ds_read_b128 v[214:217], v152 offset:23552
	global_load_lds_dwordx4 v[146:147], off
	s_add_i32 m0, s68, 0x2000
	s_add_u32 s68, s34, 0x100000
	v_lshl_add_u64 v[218:219], s[34:35], 0, v[136:137]
	s_addc_u32 s69, s35, 0
	s_add_i32 s70, s57, s41
	global_load_lds_dwordx4 v[218:219], off
	v_lshl_add_u64 v[220:221], s[68:69], 0, v[132:133]
	s_mov_b32 m0, s70
	v_lshl_add_u64 v[222:223], s[36:37], 0, v[134:135]
	global_load_lds_dwordx4 v[220:221], off
	v_lshl_add_u64 v[220:221], s[68:69], 0, v[136:137]
	s_add_i32 m0, s70, 0x2000
	s_nop 0
	global_load_lds_dwordx4 v[220:221], off
	v_lshl_add_u64 v[220:221], s[36:37], 0, v[130:131]
	s_mov_b32 m0, s29
	s_nop 0
	global_load_lds_dwordx4 v[220:221], off
	s_mov_b32 m0, s44
	s_nop 0
	global_load_lds_dwordx4 v[222:223], off
	s_waitcnt vmcnt(8)
	s_waitcnt lgkmcnt(0)
	s_barrier
	s_setprio 1
	s_waitcnt lgkmcnt(0)
	v_mfma_f32_16x16x32_bf16 v[62:65], v[154:157], v[186:189], v[62:65]
	v_mfma_f32_16x16x32_bf16 v[58:61], v[162:165], v[186:189], v[58:61]
	v_mfma_f32_16x16x32_bf16 v[54:57], v[154:157], v[194:197], v[54:57]
	v_mfma_f32_16x16x32_bf16 v[46:49], v[162:165], v[194:197], v[46:49]
	v_mfma_f32_16x16x32_bf16 v[38:41], v[154:157], v[202:205], v[38:41]
	v_mfma_f32_16x16x32_bf16 v[30:33], v[162:165], v[202:205], v[30:33]
	v_mfma_f32_16x16x32_bf16 v[22:25], v[154:157], v[210:213], v[22:25]
	v_mfma_f32_16x16x32_bf16 v[14:17], v[162:165], v[210:213], v[14:17]
	v_mfma_f32_16x16x32_bf16 v[62:65], v[158:161], v[190:193], v[62:65]
	v_mfma_f32_16x16x32_bf16 v[58:61], v[166:169], v[190:193], v[58:61]
	v_mfma_f32_16x16x32_bf16 v[54:57], v[158:161], v[198:201], v[54:57]
	v_mfma_f32_16x16x32_bf16 v[46:49], v[166:169], v[198:201], v[46:49]
	v_mfma_f32_16x16x32_bf16 v[38:41], v[158:161], v[206:209], v[38:41]
	v_mfma_f32_16x16x32_bf16 v[30:33], v[166:169], v[206:209], v[30:33]
	v_mfma_f32_16x16x32_bf16 v[22:25], v[158:161], v[214:217], v[22:25]
	v_mfma_f32_16x16x32_bf16 v[14:17], v[166:169], v[214:217], v[14:17]
	s_setprio 0
	s_setprio 1
	v_mfma_f32_16x16x32_bf16 v[50:53], v[170:173], v[186:189], v[50:53]
	v_mfma_f32_16x16x32_bf16 v[42:45], v[178:181], v[186:189], v[42:45]
	v_mfma_f32_16x16x32_bf16 v[34:37], v[170:173], v[194:197], v[34:37]
	v_mfma_f32_16x16x32_bf16 v[26:29], v[178:181], v[194:197], v[26:29]
	v_mfma_f32_16x16x32_bf16 v[18:21], v[170:173], v[202:205], v[18:21]
	v_mfma_f32_16x16x32_bf16 v[10:13], v[178:181], v[202:205], v[10:13]
	v_mfma_f32_16x16x32_bf16 v[6:9], v[170:173], v[210:213], v[6:9]
	v_mfma_f32_16x16x32_bf16 v[2:5], v[178:181], v[210:213], v[2:5]
	v_mfma_f32_16x16x32_bf16 v[50:53], v[174:177], v[190:193], v[50:53]
	v_mfma_f32_16x16x32_bf16 v[42:45], v[182:185], v[190:193], v[42:45]
	v_mfma_f32_16x16x32_bf16 v[34:37], v[174:177], v[198:201], v[34:37]
	v_mfma_f32_16x16x32_bf16 v[26:29], v[182:185], v[198:201], v[26:29]
	v_mfma_f32_16x16x32_bf16 v[18:21], v[174:177], v[206:209], v[18:21]
	v_mfma_f32_16x16x32_bf16 v[10:13], v[182:185], v[206:209], v[10:13]
	v_mfma_f32_16x16x32_bf16 v[6:9], v[174:177], v[214:217], v[6:9]
	v_mfma_f32_16x16x32_bf16 v[2:5], v[182:185], v[214:217], v[2:5]
	s_setprio 0
	s_barrier
	s_add_i32 s68, 0, 0x18000
	v_add_u32_e32 v153, s68, v148
	s_add_i32 s69, 0, 0x1c000
	ds_read_b128 v[154:157], v153
	ds_read_b128 v[158:161], v153 offset:1024
	ds_read_b128 v[162:165], v153 offset:2048
	ds_read_b128 v[166:169], v153 offset:3072
	v_add_u32_e32 v153, s69, v148
	ds_read_b128 v[170:173], v153
	ds_read_b128 v[174:177], v153 offset:1024
	ds_read_b128 v[178:181], v153 offset:2048
	ds_read_b128 v[182:185], v153 offset:3072
	s_add_u32 s36, s36, 0x100000
	s_addc_u32 s37, s37, 0
	s_mov_b32 m0, s45
	v_lshl_add_u64 v[224:225], s[36:37], 0, v[130:131]
	ds_read_b128 v[186:189], v152 offset:32768
	ds_read_b128 v[190:193], v152 offset:33792
	ds_read_b128 v[194:197], v152 offset:34816
	ds_read_b128 v[198:201], v152 offset:35840
	ds_read_b128 v[202:205], v152 offset:36864
	ds_read_b128 v[206:209], v152 offset:37888
	ds_read_b128 v[210:213], v152 offset:38912
	ds_read_b128 v[214:217], v152 offset:39936
	global_load_lds_dwordx4 v[224:225], off
	v_lshl_add_u64 v[224:225], s[36:37], 0, v[134:135]
	s_mov_b32 m0, s46
	s_nop 0
	global_load_lds_dwordx4 v[224:225], off
	s_waitcnt vmcnt(8)
	s_waitcnt lgkmcnt(0)
	s_barrier
	s_setprio 1
	s_waitcnt lgkmcnt(0)
	v_mfma_f32_16x16x32_bf16 v[126:129], v[154:157], v[186:189], v[126:129]
	v_mfma_f32_16x16x32_bf16 v[122:125], v[162:165], v[186:189], v[122:125]
	v_mfma_f32_16x16x32_bf16 v[118:121], v[154:157], v[194:197], v[118:121]
	v_mfma_f32_16x16x32_bf16 v[110:113], v[162:165], v[194:197], v[110:113]
	v_mfma_f32_16x16x32_bf16 v[102:105], v[154:157], v[202:205], v[102:105]
	v_mfma_f32_16x16x32_bf16 v[94:97], v[162:165], v[202:205], v[94:97]
	v_mfma_f32_16x16x32_bf16 v[86:89], v[154:157], v[210:213], v[86:89]
	v_mfma_f32_16x16x32_bf16 v[78:81], v[162:165], v[210:213], v[78:81]
	v_mfma_f32_16x16x32_bf16 v[126:129], v[158:161], v[190:193], v[126:129]
	v_mfma_f32_16x16x32_bf16 v[122:125], v[166:169], v[190:193], v[122:125]
	v_mfma_f32_16x16x32_bf16 v[118:121], v[158:161], v[198:201], v[118:121]
	v_mfma_f32_16x16x32_bf16 v[110:113], v[166:169], v[198:201], v[110:113]
	v_mfma_f32_16x16x32_bf16 v[102:105], v[158:161], v[206:209], v[102:105]
	v_mfma_f32_16x16x32_bf16 v[94:97], v[166:169], v[206:209], v[94:97]
	v_mfma_f32_16x16x32_bf16 v[86:89], v[158:161], v[214:217], v[86:89]
	v_mfma_f32_16x16x32_bf16 v[78:81], v[166:169], v[214:217], v[78:81]
	s_setprio 0
	s_setprio 1
	v_mfma_f32_16x16x32_bf16 v[114:117], v[170:173], v[186:189], v[114:117]
	v_mfma_f32_16x16x32_bf16 v[106:109], v[178:181], v[186:189], v[106:109]
	v_mfma_f32_16x16x32_bf16 v[98:101], v[170:173], v[194:197], v[98:101]
	v_mfma_f32_16x16x32_bf16 v[90:93], v[178:181], v[194:197], v[90:93]
	v_mfma_f32_16x16x32_bf16 v[82:85], v[170:173], v[202:205], v[82:85]
	v_mfma_f32_16x16x32_bf16 v[74:77], v[178:181], v[202:205], v[74:77]
	v_mfma_f32_16x16x32_bf16 v[70:73], v[170:173], v[210:213], v[70:73]
	v_mfma_f32_16x16x32_bf16 v[66:69], v[178:181], v[210:213], v[66:69]
	v_mfma_f32_16x16x32_bf16 v[114:117], v[174:177], v[190:193], v[114:117]
	v_mfma_f32_16x16x32_bf16 v[106:109], v[182:185], v[190:193], v[106:109]
	v_mfma_f32_16x16x32_bf16 v[98:101], v[174:177], v[198:201], v[98:101]
	v_mfma_f32_16x16x32_bf16 v[90:93], v[182:185], v[198:201], v[90:93]
	v_mfma_f32_16x16x32_bf16 v[82:85], v[174:177], v[206:209], v[82:85]
	v_mfma_f32_16x16x32_bf16 v[74:77], v[182:185], v[206:209], v[74:77]
	v_mfma_f32_16x16x32_bf16 v[70:73], v[174:177], v[214:217], v[70:73]
	v_mfma_f32_16x16x32_bf16 v[66:69], v[182:185], v[214:217], v[66:69]
	s_setprio 0
	s_barrier
	s_add_i32 s36, s68, s41
	v_lshl_add_u64 v[146:147], v[146:147], 0, s[8:9]
	s_mov_b32 m0, s36
	ds_read_b128 v[186:189], v152 offset:49152
	ds_read_b128 v[190:193], v152 offset:50176
	ds_read_b128 v[194:197], v152 offset:51200
	ds_read_b128 v[198:201], v152 offset:52224
	ds_read_b128 v[202:205], v152 offset:53248
	ds_read_b128 v[206:209], v152 offset:54272
	ds_read_b128 v[210:213], v152 offset:55296
	ds_read_b128 v[214:217], v152 offset:56320
	global_load_lds_dwordx4 v[146:147], off
	s_add_i32 m0, s36, 0x2000
	s_add_u32 s34, s34, 0x100080
	v_lshl_add_u64 v[146:147], v[218:219], 0, s[8:9]
	s_addc_u32 s35, s35, 0
	s_add_i32 s36, s69, s41
	global_load_lds_dwordx4 v[146:147], off
	v_lshl_add_u64 v[146:147], s[34:35], 0, v[132:133]
	s_mov_b32 m0, s36
	s_nop 0
	global_load_lds_dwordx4 v[146:147], off
	v_lshl_add_u64 v[146:147], s[34:35], 0, v[136:137]
	s_add_i32 m0, s36, 0x2000
	s_nop 0
	global_load_lds_dwordx4 v[146:147], off
	v_lshl_add_u64 v[146:147], v[220:221], 0, s[8:9]
	s_mov_b32 m0, s52
	s_nop 0
	global_load_lds_dwordx4 v[146:147], off
	v_lshl_add_u64 v[146:147], v[222:223], 0, s[8:9]
	s_mov_b32 m0, s53
	s_nop 0
	global_load_lds_dwordx4 v[146:147], off
	s_waitcnt vmcnt(8)
	s_waitcnt lgkmcnt(0)
	s_barrier
	s_add_i32 s67, s67, 2
	s_add_u32 s30, s30, 0x100
	s_addc_u32 s31, s31, 0
	s_add_u32 s65, s65, 0x100
	s_addc_u32 s66, s66, 0
	s_cmp_gt_u32 s67, 61
	s_setprio 1
	s_waitcnt lgkmcnt(0)
	v_mfma_f32_16x16x32_bf16 v[62:65], v[154:157], v[186:189], v[62:65]
	v_mfma_f32_16x16x32_bf16 v[58:61], v[162:165], v[186:189], v[58:61]
	v_mfma_f32_16x16x32_bf16 v[54:57], v[154:157], v[194:197], v[54:57]
	v_mfma_f32_16x16x32_bf16 v[46:49], v[162:165], v[194:197], v[46:49]
	v_mfma_f32_16x16x32_bf16 v[38:41], v[154:157], v[202:205], v[38:41]
	v_mfma_f32_16x16x32_bf16 v[30:33], v[162:165], v[202:205], v[30:33]
	v_mfma_f32_16x16x32_bf16 v[22:25], v[154:157], v[210:213], v[22:25]
	v_mfma_f32_16x16x32_bf16 v[14:17], v[162:165], v[210:213], v[14:17]
	v_mfma_f32_16x16x32_bf16 v[62:65], v[158:161], v[190:193], v[62:65]
	v_mfma_f32_16x16x32_bf16 v[58:61], v[166:169], v[190:193], v[58:61]
	v_mfma_f32_16x16x32_bf16 v[54:57], v[158:161], v[198:201], v[54:57]
	v_mfma_f32_16x16x32_bf16 v[46:49], v[166:169], v[198:201], v[46:49]
	v_mfma_f32_16x16x32_bf16 v[38:41], v[158:161], v[206:209], v[38:41]
	v_mfma_f32_16x16x32_bf16 v[30:33], v[166:169], v[206:209], v[30:33]
	v_mfma_f32_16x16x32_bf16 v[22:25], v[158:161], v[214:217], v[22:25]
	v_mfma_f32_16x16x32_bf16 v[14:17], v[166:169], v[214:217], v[14:17]
	s_setprio 0
	s_setprio 1
	v_mfma_f32_16x16x32_bf16 v[50:53], v[170:173], v[186:189], v[50:53]
	v_mfma_f32_16x16x32_bf16 v[42:45], v[178:181], v[186:189], v[42:45]
	v_mfma_f32_16x16x32_bf16 v[34:37], v[170:173], v[194:197], v[34:37]
	v_mfma_f32_16x16x32_bf16 v[26:29], v[178:181], v[194:197], v[26:29]
	v_mfma_f32_16x16x32_bf16 v[18:21], v[170:173], v[202:205], v[18:21]
	v_mfma_f32_16x16x32_bf16 v[10:13], v[178:181], v[202:205], v[10:13]
	v_mfma_f32_16x16x32_bf16 v[6:9], v[170:173], v[210:213], v[6:9]
	v_mfma_f32_16x16x32_bf16 v[2:5], v[178:181], v[210:213], v[2:5]
	v_mfma_f32_16x16x32_bf16 v[50:53], v[174:177], v[190:193], v[50:53]
	v_mfma_f32_16x16x32_bf16 v[42:45], v[182:185], v[190:193], v[42:45]
	v_mfma_f32_16x16x32_bf16 v[34:37], v[174:177], v[198:201], v[34:37]
	v_mfma_f32_16x16x32_bf16 v[26:29], v[182:185], v[198:201], v[26:29]
	v_mfma_f32_16x16x32_bf16 v[18:21], v[174:177], v[206:209], v[18:21]
	v_mfma_f32_16x16x32_bf16 v[10:13], v[182:185], v[206:209], v[10:13]
	v_mfma_f32_16x16x32_bf16 v[6:9], v[174:177], v[214:217], v[6:9]
	v_mfma_f32_16x16x32_bf16 v[2:5], v[182:185], v[214:217], v[2:5]
	s_setprio 0
	s_barrier
	s_cbranch_scc0 .LBB0_728
	s_and_b64 vcc, exec, s[10:11]
	s_cbranch_vccz .LBB0_731
	s_barrier

.LBB0_855:
	ds_read_b128 v[146:149], v152
	ds_read_b128 v[156:159], v152 offset:1024
	ds_read_b128 v[160:163], v152 offset:2048
	ds_read_b128 v[164:167], v152 offset:3072
	ds_read_b128 v[168:171], v153
	ds_read_b128 v[172:175], v153 offset:1024
	ds_read_b128 v[176:179], v153 offset:2048
	ds_read_b128 v[180:183], v153 offset:3072
	s_add_u32 s24, s22, 0xfffc0080
	s_addc_u32 s25, s23, -1
	s_cmp_eq_u32 s57, 12
	s_cselect_b32 s27, s15, s25
	s_cselect_b32 s26, s53, s24
	s_cselect_b32 s25, s13, s56
	s_cselect_b32 s24, s54, s55
	v_lshl_add_u64 v[216:217], s[22:23], 0, v[138:139]
	s_add_i32 m0, s21, 0xc000
	ds_read_b128 v[184:187], v154
	ds_read_b128 v[188:191], v154 offset:1024
	ds_read_b128 v[192:195], v154 offset:2048
	ds_read_b128 v[196:199], v154 offset:3072
	ds_read_b128 v[200:203], v154 offset:4096
	ds_read_b128 v[204:207], v154 offset:5120
	ds_read_b128 v[208:211], v154 offset:6144
	ds_read_b128 v[212:215], v154 offset:7168
	global_load_lds_dwordx4 v[216:217], off
	v_lshl_add_u64 v[216:217], s[22:23], 0, v[140:141]
	s_add_i32 m0, s21, 0xe000
	s_nop 0
	global_load_lds_dwordx4 v[216:217], off
	s_waitcnt vmcnt(8)
	s_waitcnt lgkmcnt(0)
	s_barrier
	s_setprio 1
	s_waitcnt lgkmcnt(0)
	v_mfma_f32_16x16x32_bf16 v[126:129], v[146:149], v[184:187], v[126:129]
	v_mfma_f32_16x16x32_bf16 v[122:125], v[160:163], v[184:187], v[122:125]
	v_mfma_f32_16x16x32_bf16 v[118:121], v[146:149], v[192:195], v[118:121]
	v_mfma_f32_16x16x32_bf16 v[110:113], v[160:163], v[192:195], v[110:113]
	v_mfma_f32_16x16x32_bf16 v[102:105], v[146:149], v[200:203], v[102:105]
	v_mfma_f32_16x16x32_bf16 v[94:97], v[160:163], v[200:203], v[94:97]
	v_mfma_f32_16x16x32_bf16 v[86:89], v[146:149], v[208:211], v[86:89]
	v_mfma_f32_16x16x32_bf16 v[78:81], v[160:163], v[208:211], v[78:81]
	v_mfma_f32_16x16x32_bf16 v[126:129], v[156:159], v[188:191], v[126:129]
	v_mfma_f32_16x16x32_bf16 v[122:125], v[164:167], v[188:191], v[122:125]
	v_mfma_f32_16x16x32_bf16 v[118:121], v[156:159], v[196:199], v[118:121]
	v_mfma_f32_16x16x32_bf16 v[110:113], v[164:167], v[196:199], v[110:113]
	v_mfma_f32_16x16x32_bf16 v[102:105], v[156:159], v[204:207], v[102:105]
	v_mfma_f32_16x16x32_bf16 v[94:97], v[164:167], v[204:207], v[94:97]
	v_mfma_f32_16x16x32_bf16 v[86:89], v[156:159], v[212:215], v[86:89]
	v_mfma_f32_16x16x32_bf16 v[78:81], v[164:167], v[212:215], v[78:81]
	s_setprio 0
	s_setprio 1
	v_mfma_f32_16x16x32_bf16 v[114:117], v[168:171], v[184:187], v[114:117]
	v_mfma_f32_16x16x32_bf16 v[106:109], v[176:179], v[184:187], v[106:109]
	v_mfma_f32_16x16x32_bf16 v[98:101], v[168:171], v[192:195], v[98:101]
	v_mfma_f32_16x16x32_bf16 v[90:93], v[176:179], v[192:195], v[90:93]
	v_mfma_f32_16x16x32_bf16 v[82:85], v[168:171], v[200:203], v[82:85]
	v_mfma_f32_16x16x32_bf16 v[74:77], v[176:179], v[200:203], v[74:77]
	v_mfma_f32_16x16x32_bf16 v[70:73], v[168:171], v[208:211], v[70:73]
	v_mfma_f32_16x16x32_bf16 v[66:69], v[176:179], v[208:211], v[66:69]
	v_mfma_f32_16x16x32_bf16 v[114:117], v[172:175], v[188:191], v[114:117]
	v_mfma_f32_16x16x32_bf16 v[106:109], v[180:183], v[188:191], v[106:109]
	v_mfma_f32_16x16x32_bf16 v[98:101], v[172:175], v[196:199], v[98:101]
	v_mfma_f32_16x16x32_bf16 v[90:93], v[180:183], v[196:199], v[90:93]
	v_mfma_f32_16x16x32_bf16 v[82:85], v[172:175], v[204:207], v[82:85]
	v_mfma_f32_16x16x32_bf16 v[74:77], v[180:183], v[204:207], v[74:77]
	v_mfma_f32_16x16x32_bf16 v[70:73], v[172:175], v[212:215], v[70:73]
	v_mfma_f32_16x16x32_bf16 v[66:69], v[180:183], v[212:215], v[66:69]
	s_setprio 0
	s_barrier
	s_add_i32 s58, s45, s31
	v_lshl_add_u64 v[216:217], s[24:25], 0, v[134:135]
	s_mov_b32 m0, s58
	ds_read_b128 v[184:187], v154 offset:16384
	ds_read_b128 v[188:191], v154 offset:17408
	ds_read_b128 v[192:195], v154 offset:18432
	ds_read_b128 v[196:199], v154 offset:19456
	ds_read_b128 v[200:203], v154 offset:20480
	ds_read_b128 v[204:207], v154 offset:21504
	ds_read_b128 v[208:211], v154 offset:22528
	ds_read_b128 v[212:215], v154 offset:23552
	global_load_lds_dwordx4 v[216:217], off
	s_add_i32 m0, s58, 0x2000
	s_add_u32 s58, s24, 0x40000
	v_lshl_add_u64 v[218:219], s[24:25], 0, v[130:131]
	s_addc_u32 s59, s25, 0
	s_add_i32 s60, s46, s31
	global_load_lds_dwordx4 v[218:219], off
	v_lshl_add_u64 v[220:221], s[58:59], 0, v[134:135]
	s_mov_b32 m0, s60
	v_lshl_add_u64 v[222:223], s[26:27], 0, v[132:133]
	global_load_lds_dwordx4 v[220:221], off
	v_lshl_add_u64 v[220:221], s[58:59], 0, v[130:131]
	s_add_i32 m0, s60, 0x2000
	s_nop 0
	global_load_lds_dwordx4 v[220:221], off
	v_lshl_add_u64 v[220:221], s[26:27], 0, v[136:137]
	s_mov_b32 m0, s21
	s_nop 0
	global_load_lds_dwordx4 v[220:221], off
	s_mov_b32 m0, s35
	s_nop 0
	global_load_lds_dwordx4 v[222:223], off
	s_waitcnt vmcnt(8)
	s_waitcnt lgkmcnt(0)
	s_barrier
	s_setprio 1
	s_waitcnt lgkmcnt(0)
	v_mfma_f32_16x16x32_bf16 v[62:65], v[146:149], v[184:187], v[62:65]
	v_mfma_f32_16x16x32_bf16 v[58:61], v[160:163], v[184:187], v[58:61]
	v_mfma_f32_16x16x32_bf16 v[54:57], v[146:149], v[192:195], v[54:57]
	v_mfma_f32_16x16x32_bf16 v[46:49], v[160:163], v[192:195], v[46:49]
	v_mfma_f32_16x16x32_bf16 v[38:41], v[146:149], v[200:203], v[38:41]
	v_mfma_f32_16x16x32_bf16 v[30:33], v[160:163], v[200:203], v[30:33]
	v_mfma_f32_16x16x32_bf16 v[22:25], v[146:149], v[208:211], v[22:25]
	v_mfma_f32_16x16x32_bf16 v[14:17], v[160:163], v[208:211], v[14:17]
	v_mfma_f32_16x16x32_bf16 v[62:65], v[156:159], v[188:191], v[62:65]
	v_mfma_f32_16x16x32_bf16 v[58:61], v[164:167], v[188:191], v[58:61]
	v_mfma_f32_16x16x32_bf16 v[54:57], v[156:159], v[196:199], v[54:57]
	v_mfma_f32_16x16x32_bf16 v[46:49], v[164:167], v[196:199], v[46:49]
	v_mfma_f32_16x16x32_bf16 v[38:41], v[156:159], v[204:207], v[38:41]
	v_mfma_f32_16x16x32_bf16 v[30:33], v[164:167], v[204:207], v[30:33]
	v_mfma_f32_16x16x32_bf16 v[22:25], v[156:159], v[212:215], v[22:25]
	v_mfma_f32_16x16x32_bf16 v[14:17], v[164:167], v[212:215], v[14:17]
	s_setprio 0
	s_setprio 1
	v_mfma_f32_16x16x32_bf16 v[50:53], v[168:171], v[184:187], v[50:53]
	v_mfma_f32_16x16x32_bf16 v[42:45], v[176:179], v[184:187], v[42:45]
	v_mfma_f32_16x16x32_bf16 v[34:37], v[168:171], v[192:195], v[34:37]
	v_mfma_f32_16x16x32_bf16 v[26:29], v[176:179], v[192:195], v[26:29]
	v_mfma_f32_16x16x32_bf16 v[18:21], v[168:171], v[200:203], v[18:21]
	v_mfma_f32_16x16x32_bf16 v[10:13], v[176:179], v[200:203], v[10:13]
	v_mfma_f32_16x16x32_bf16 v[6:9], v[168:171], v[208:211], v[6:9]
	v_mfma_f32_16x16x32_bf16 v[2:5], v[176:179], v[208:211], v[2:5]
	v_mfma_f32_16x16x32_bf16 v[50:53], v[172:175], v[188:191], v[50:53]
	v_mfma_f32_16x16x32_bf16 v[42:45], v[180:183], v[188:191], v[42:45]
	v_mfma_f32_16x16x32_bf16 v[34:37], v[172:175], v[196:199], v[34:37]
	v_mfma_f32_16x16x32_bf16 v[26:29], v[180:183], v[196:199], v[26:29]
	v_mfma_f32_16x16x32_bf16 v[18:21], v[172:175], v[204:207], v[18:21]
	v_mfma_f32_16x16x32_bf16 v[10:13], v[180:183], v[204:207], v[10:13]
	v_mfma_f32_16x16x32_bf16 v[6:9], v[172:175], v[212:215], v[6:9]
	v_mfma_f32_16x16x32_bf16 v[2:5], v[180:183], v[212:215], v[2:5]
	s_setprio 0
	s_barrier
	s_add_i32 s58, 0, 0x18000
	v_add_u32_e32 v155, s58, v150
	s_add_i32 s59, 0, 0x1c000
	ds_read_b128 v[146:149], v155
	ds_read_b128 v[156:159], v155 offset:1024
	ds_read_b128 v[160:163], v155 offset:2048
	ds_read_b128 v[164:167], v155 offset:3072
	v_add_u32_e32 v155, s59, v150
	ds_read_b128 v[168:171], v155
	ds_read_b128 v[172:175], v155 offset:1024
	ds_read_b128 v[176:179], v155 offset:2048
	ds_read_b128 v[180:183], v155 offset:3072
	s_add_u32 s26, s26, 0x40000
	s_addc_u32 s27, s27, 0
	s_mov_b32 m0, s36
	v_lshl_add_u64 v[224:225], s[26:27], 0, v[136:137]
	ds_read_b128 v[184:187], v154 offset:32768
	ds_read_b128 v[188:191], v154 offset:33792
	ds_read_b128 v[192:195], v154 offset:34816
	ds_read_b128 v[196:199], v154 offset:35840
	ds_read_b128 v[200:203], v154 offset:36864
	ds_read_b128 v[204:207], v154 offset:37888
	ds_read_b128 v[208:211], v154 offset:38912
	ds_read_b128 v[212:215], v154 offset:39936
	global_load_lds_dwordx4 v[224:225], off
	v_lshl_add_u64 v[224:225], s[26:27], 0, v[132:133]
	s_mov_b32 m0, s37
	s_nop 0
	global_load_lds_dwordx4 v[224:225], off
	s_waitcnt vmcnt(8)
	s_waitcnt lgkmcnt(0)
	s_barrier
	s_setprio 1
	s_waitcnt lgkmcnt(0)
	v_mfma_f32_16x16x32_bf16 v[126:129], v[146:149], v[184:187], v[126:129]
	v_mfma_f32_16x16x32_bf16 v[122:125], v[160:163], v[184:187], v[122:125]
	v_mfma_f32_16x16x32_bf16 v[118:121], v[146:149], v[192:195], v[118:121]
	v_mfma_f32_16x16x32_bf16 v[110:113], v[160:163], v[192:195], v[110:113]
	v_mfma_f32_16x16x32_bf16 v[102:105], v[146:149], v[200:203], v[102:105]
	v_mfma_f32_16x16x32_bf16 v[94:97], v[160:163], v[200:203], v[94:97]
	v_mfma_f32_16x16x32_bf16 v[86:89], v[146:149], v[208:211], v[86:89]
	v_mfma_f32_16x16x32_bf16 v[78:81], v[160:163], v[208:211], v[78:81]
	v_mfma_f32_16x16x32_bf16 v[126:129], v[156:159], v[188:191], v[126:129]
	v_mfma_f32_16x16x32_bf16 v[122:125], v[164:167], v[188:191], v[122:125]
	v_mfma_f32_16x16x32_bf16 v[118:121], v[156:159], v[196:199], v[118:121]
	v_mfma_f32_16x16x32_bf16 v[110:113], v[164:167], v[196:199], v[110:113]
	v_mfma_f32_16x16x32_bf16 v[102:105], v[156:159], v[204:207], v[102:105]
	v_mfma_f32_16x16x32_bf16 v[94:97], v[164:167], v[204:207], v[94:97]
	v_mfma_f32_16x16x32_bf16 v[86:89], v[156:159], v[212:215], v[86:89]
	v_mfma_f32_16x16x32_bf16 v[78:81], v[164:167], v[212:215], v[78:81]
	s_setprio 0
	s_setprio 1
	v_mfma_f32_16x16x32_bf16 v[114:117], v[168:171], v[184:187], v[114:117]
	v_mfma_f32_16x16x32_bf16 v[106:109], v[176:179], v[184:187], v[106:109]
	v_mfma_f32_16x16x32_bf16 v[98:101], v[168:171], v[192:195], v[98:101]
	v_mfma_f32_16x16x32_bf16 v[90:93], v[176:179], v[192:195], v[90:93]
	v_mfma_f32_16x16x32_bf16 v[82:85], v[168:171], v[200:203], v[82:85]
	v_mfma_f32_16x16x32_bf16 v[74:77], v[176:179], v[200:203], v[74:77]
	v_mfma_f32_16x16x32_bf16 v[70:73], v[168:171], v[208:211], v[70:73]
	v_mfma_f32_16x16x32_bf16 v[66:69], v[176:179], v[208:211], v[66:69]
	v_mfma_f32_16x16x32_bf16 v[114:117], v[172:175], v[188:191], v[114:117]
	v_mfma_f32_16x16x32_bf16 v[106:109], v[180:183], v[188:191], v[106:109]
	v_mfma_f32_16x16x32_bf16 v[98:101], v[172:175], v[196:199], v[98:101]
	v_mfma_f32_16x16x32_bf16 v[90:93], v[180:183], v[196:199], v[90:93]
	v_mfma_f32_16x16x32_bf16 v[82:85], v[172:175], v[204:207], v[82:85]
	v_mfma_f32_16x16x32_bf16 v[74:77], v[180:183], v[204:207], v[74:77]
	v_mfma_f32_16x16x32_bf16 v[70:73], v[172:175], v[212:215], v[70:73]
	v_mfma_f32_16x16x32_bf16 v[66:69], v[180:183], v[212:215], v[66:69]
	s_setprio 0
	s_barrier
	s_add_i32 s26, s58, s31
	v_lshl_add_u64 v[216:217], v[216:217], 0, s[8:9]
	s_mov_b32 m0, s26
	ds_read_b128 v[184:187], v154 offset:49152
	ds_read_b128 v[188:191], v154 offset:50176
	ds_read_b128 v[192:195], v154 offset:51200
	ds_read_b128 v[196:199], v154 offset:52224
	ds_read_b128 v[200:203], v154 offset:53248
	ds_read_b128 v[204:207], v154 offset:54272
	ds_read_b128 v[208:211], v154 offset:55296
	ds_read_b128 v[212:215], v154 offset:56320
	global_load_lds_dwordx4 v[216:217], off
	s_add_i32 m0, s26, 0x2000
	s_add_u32 s24, s24, 0x40080
	v_lshl_add_u64 v[216:217], v[218:219], 0, s[8:9]
	s_addc_u32 s25, s25, 0
	s_add_i32 s26, s59, s31
	global_load_lds_dwordx4 v[216:217], off
	v_lshl_add_u64 v[216:217], s[24:25], 0, v[134:135]
	s_mov_b32 m0, s26
	s_nop 0
	global_load_lds_dwordx4 v[216:217], off
	v_lshl_add_u64 v[216:217], s[24:25], 0, v[130:131]
	s_add_i32 m0, s26, 0x2000
	s_nop 0
	global_load_lds_dwordx4 v[216:217], off
	v_lshl_add_u64 v[216:217], v[220:221], 0, s[8:9]
	s_mov_b32 m0, s39
	s_nop 0
	global_load_lds_dwordx4 v[216:217], off
	v_lshl_add_u64 v[216:217], v[222:223], 0, s[8:9]
	s_mov_b32 m0, s40
	s_nop 0
	global_load_lds_dwordx4 v[216:217], off
	s_waitcnt vmcnt(8)
	s_waitcnt lgkmcnt(0)
	s_barrier
	s_add_i32 s57, s57, 2
	s_add_u32 s22, s22, 0x100
	s_addc_u32 s23, s23, 0
	s_add_u32 s55, s55, 0x100
	s_addc_u32 s56, s56, 0
	s_cmp_gt_u32 s57, 13
	s_setprio 1
	s_waitcnt lgkmcnt(0)
	v_mfma_f32_16x16x32_bf16 v[62:65], v[146:149], v[184:187], v[62:65]
	v_mfma_f32_16x16x32_bf16 v[58:61], v[160:163], v[184:187], v[58:61]
	v_mfma_f32_16x16x32_bf16 v[54:57], v[146:149], v[192:195], v[54:57]
	v_mfma_f32_16x16x32_bf16 v[46:49], v[160:163], v[192:195], v[46:49]
	v_mfma_f32_16x16x32_bf16 v[38:41], v[146:149], v[200:203], v[38:41]
	v_mfma_f32_16x16x32_bf16 v[30:33], v[160:163], v[200:203], v[30:33]
	v_mfma_f32_16x16x32_bf16 v[22:25], v[146:149], v[208:211], v[22:25]
	v_mfma_f32_16x16x32_bf16 v[14:17], v[160:163], v[208:211], v[14:17]
	v_mfma_f32_16x16x32_bf16 v[62:65], v[156:159], v[188:191], v[62:65]
	v_mfma_f32_16x16x32_bf16 v[58:61], v[164:167], v[188:191], v[58:61]
	v_mfma_f32_16x16x32_bf16 v[54:57], v[156:159], v[196:199], v[54:57]
	v_mfma_f32_16x16x32_bf16 v[46:49], v[164:167], v[196:199], v[46:49]
	v_mfma_f32_16x16x32_bf16 v[38:41], v[156:159], v[204:207], v[38:41]
	v_mfma_f32_16x16x32_bf16 v[30:33], v[164:167], v[204:207], v[30:33]
	v_mfma_f32_16x16x32_bf16 v[22:25], v[156:159], v[212:215], v[22:25]
	v_mfma_f32_16x16x32_bf16 v[14:17], v[164:167], v[212:215], v[14:17]
	s_setprio 0
	s_setprio 1
	v_mfma_f32_16x16x32_bf16 v[50:53], v[168:171], v[184:187], v[50:53]
	v_mfma_f32_16x16x32_bf16 v[42:45], v[176:179], v[184:187], v[42:45]
	v_mfma_f32_16x16x32_bf16 v[34:37], v[168:171], v[192:195], v[34:37]
	v_mfma_f32_16x16x32_bf16 v[26:29], v[176:179], v[192:195], v[26:29]
	v_mfma_f32_16x16x32_bf16 v[18:21], v[168:171], v[200:203], v[18:21]
	v_mfma_f32_16x16x32_bf16 v[10:13], v[176:179], v[200:203], v[10:13]
	v_mfma_f32_16x16x32_bf16 v[6:9], v[168:171], v[208:211], v[6:9]
	v_mfma_f32_16x16x32_bf16 v[2:5], v[176:179], v[208:211], v[2:5]
	v_mfma_f32_16x16x32_bf16 v[50:53], v[172:175], v[188:191], v[50:53]
	v_mfma_f32_16x16x32_bf16 v[42:45], v[180:183], v[188:191], v[42:45]
	v_mfma_f32_16x16x32_bf16 v[34:37], v[172:175], v[196:199], v[34:37]
	v_mfma_f32_16x16x32_bf16 v[26:29], v[180:183], v[196:199], v[26:29]
	v_mfma_f32_16x16x32_bf16 v[18:21], v[172:175], v[204:207], v[18:21]
	v_mfma_f32_16x16x32_bf16 v[10:13], v[180:183], v[204:207], v[10:13]
	v_mfma_f32_16x16x32_bf16 v[6:9], v[172:175], v[212:215], v[6:9]
	v_mfma_f32_16x16x32_bf16 v[2:5], v[180:183], v[212:215], v[2:5]
	s_setprio 0
	s_barrier
	s_cbranch_scc0 .LBB0_855
	s_and_b64 vcc, exec, s[10:11]
	s_cbranch_vccz .LBB0_858
	s_barrier

.LBB0_1031:
	ds_read_b128 v[154:157], v150
	ds_read_b128 v[158:161], v150 offset:1024
	ds_read_b128 v[162:165], v150 offset:2048
	ds_read_b128 v[166:169], v150 offset:3072
	ds_read_b128 v[170:173], v151
	ds_read_b128 v[174:177], v151 offset:1024
	ds_read_b128 v[178:181], v151 offset:2048
	ds_read_b128 v[182:185], v151 offset:3072
	s_add_u32 s34, s30, 0xfffc0080
	s_addc_u32 s35, s31, -1
	s_cmp_eq_u32 s65, 12
	s_cselect_b32 s37, s23, s35
	s_cselect_b32 s36, s61, s34
	s_cselect_b32 s35, s21, s64
	s_cselect_b32 s34, s62, s63
	v_lshl_add_u64 v[146:147], s[30:31], 0, v[138:139]
	s_add_i32 m0, s29, 0xc000
	ds_read_b128 v[186:189], v152
	ds_read_b128 v[190:193], v152 offset:1024
	ds_read_b128 v[194:197], v152 offset:2048
	ds_read_b128 v[198:201], v152 offset:3072
	ds_read_b128 v[202:205], v152 offset:4096
	ds_read_b128 v[206:209], v152 offset:5120
	ds_read_b128 v[210:213], v152 offset:6144
	ds_read_b128 v[214:217], v152 offset:7168
	global_load_lds_dwordx4 v[146:147], off
	v_lshl_add_u64 v[146:147], s[30:31], 0, v[140:141]
	s_add_i32 m0, s29, 0xe000
	s_nop 0
	global_load_lds_dwordx4 v[146:147], off
	s_waitcnt vmcnt(8)
	s_waitcnt lgkmcnt(0)
	s_barrier
	s_setprio 1
	s_waitcnt lgkmcnt(0)
	v_mfma_f32_16x16x32_bf16 v[126:129], v[154:157], v[186:189], v[126:129]
	v_mfma_f32_16x16x32_bf16 v[122:125], v[162:165], v[186:189], v[122:125]
	v_mfma_f32_16x16x32_bf16 v[118:121], v[154:157], v[194:197], v[118:121]
	v_mfma_f32_16x16x32_bf16 v[110:113], v[162:165], v[194:197], v[110:113]
	v_mfma_f32_16x16x32_bf16 v[102:105], v[154:157], v[202:205], v[102:105]
	v_mfma_f32_16x16x32_bf16 v[94:97], v[162:165], v[202:205], v[94:97]
	v_mfma_f32_16x16x32_bf16 v[86:89], v[154:157], v[210:213], v[86:89]
	v_mfma_f32_16x16x32_bf16 v[78:81], v[162:165], v[210:213], v[78:81]
	v_mfma_f32_16x16x32_bf16 v[126:129], v[158:161], v[190:193], v[126:129]
	v_mfma_f32_16x16x32_bf16 v[122:125], v[166:169], v[190:193], v[122:125]
	v_mfma_f32_16x16x32_bf16 v[118:121], v[158:161], v[198:201], v[118:121]
	v_mfma_f32_16x16x32_bf16 v[110:113], v[166:169], v[198:201], v[110:113]
	v_mfma_f32_16x16x32_bf16 v[102:105], v[158:161], v[206:209], v[102:105]
	v_mfma_f32_16x16x32_bf16 v[94:97], v[166:169], v[206:209], v[94:97]
	v_mfma_f32_16x16x32_bf16 v[86:89], v[158:161], v[214:217], v[86:89]
	v_mfma_f32_16x16x32_bf16 v[78:81], v[166:169], v[214:217], v[78:81]
	s_setprio 0
	s_setprio 1
	v_mfma_f32_16x16x32_bf16 v[114:117], v[170:173], v[186:189], v[114:117]
	v_mfma_f32_16x16x32_bf16 v[106:109], v[178:181], v[186:189], v[106:109]
	v_mfma_f32_16x16x32_bf16 v[98:101], v[170:173], v[194:197], v[98:101]
	v_mfma_f32_16x16x32_bf16 v[90:93], v[178:181], v[194:197], v[90:93]
	v_mfma_f32_16x16x32_bf16 v[82:85], v[170:173], v[202:205], v[82:85]
	v_mfma_f32_16x16x32_bf16 v[74:77], v[178:181], v[202:205], v[74:77]
	v_mfma_f32_16x16x32_bf16 v[70:73], v[170:173], v[210:213], v[70:73]
	v_mfma_f32_16x16x32_bf16 v[66:69], v[178:181], v[210:213], v[66:69]
	v_mfma_f32_16x16x32_bf16 v[114:117], v[174:177], v[190:193], v[114:117]
	v_mfma_f32_16x16x32_bf16 v[106:109], v[182:185], v[190:193], v[106:109]
	v_mfma_f32_16x16x32_bf16 v[98:101], v[174:177], v[198:201], v[98:101]
	v_mfma_f32_16x16x32_bf16 v[90:93], v[182:185], v[198:201], v[90:93]
	v_mfma_f32_16x16x32_bf16 v[82:85], v[174:177], v[206:209], v[82:85]
	v_mfma_f32_16x16x32_bf16 v[74:77], v[182:185], v[206:209], v[74:77]
	v_mfma_f32_16x16x32_bf16 v[70:73], v[174:177], v[214:217], v[70:73]
	v_mfma_f32_16x16x32_bf16 v[66:69], v[182:185], v[214:217], v[66:69]
	s_setprio 0
	s_barrier
	s_add_i32 s66, s54, s41
	v_lshl_add_u64 v[146:147], s[34:35], 0, v[132:133]
	s_mov_b32 m0, s66
	ds_read_b128 v[186:189], v152 offset:16384
	ds_read_b128 v[190:193], v152 offset:17408
	ds_read_b128 v[194:197], v152 offset:18432
	ds_read_b128 v[198:201], v152 offset:19456
	ds_read_b128 v[202:205], v152 offset:20480
	ds_read_b128 v[206:209], v152 offset:21504
	ds_read_b128 v[210:213], v152 offset:22528
	ds_read_b128 v[214:217], v152 offset:23552
	global_load_lds_dwordx4 v[146:147], off
	s_add_i32 m0, s66, 0x2000
	s_add_u32 s66, s34, 0x40000
	v_lshl_add_u64 v[218:219], s[34:35], 0, v[136:137]
	s_addc_u32 s67, s35, 0
	s_add_i32 s68, s55, s41
	global_load_lds_dwordx4 v[218:219], off
	v_lshl_add_u64 v[220:221], s[66:67], 0, v[132:133]
	s_mov_b32 m0, s68
	v_lshl_add_u64 v[222:223], s[36:37], 0, v[134:135]
	global_load_lds_dwordx4 v[220:221], off
	v_lshl_add_u64 v[220:221], s[66:67], 0, v[136:137]
	s_add_i32 m0, s68, 0x2000
	s_nop 0
	global_load_lds_dwordx4 v[220:221], off
	v_lshl_add_u64 v[220:221], s[36:37], 0, v[130:131]
	s_mov_b32 m0, s29
	s_nop 0
	global_load_lds_dwordx4 v[220:221], off
	s_mov_b32 m0, s42
	s_nop 0
	global_load_lds_dwordx4 v[222:223], off
	s_waitcnt vmcnt(8)
	s_waitcnt lgkmcnt(0)
	s_barrier
	s_setprio 1
	s_waitcnt lgkmcnt(0)
	v_mfma_f32_16x16x32_bf16 v[62:65], v[154:157], v[186:189], v[62:65]
	v_mfma_f32_16x16x32_bf16 v[58:61], v[162:165], v[186:189], v[58:61]
	v_mfma_f32_16x16x32_bf16 v[54:57], v[154:157], v[194:197], v[54:57]
	v_mfma_f32_16x16x32_bf16 v[46:49], v[162:165], v[194:197], v[46:49]
	v_mfma_f32_16x16x32_bf16 v[38:41], v[154:157], v[202:205], v[38:41]
	v_mfma_f32_16x16x32_bf16 v[30:33], v[162:165], v[202:205], v[30:33]
	v_mfma_f32_16x16x32_bf16 v[22:25], v[154:157], v[210:213], v[22:25]
	v_mfma_f32_16x16x32_bf16 v[14:17], v[162:165], v[210:213], v[14:17]
	v_mfma_f32_16x16x32_bf16 v[62:65], v[158:161], v[190:193], v[62:65]
	v_mfma_f32_16x16x32_bf16 v[58:61], v[166:169], v[190:193], v[58:61]
	v_mfma_f32_16x16x32_bf16 v[54:57], v[158:161], v[198:201], v[54:57]
	v_mfma_f32_16x16x32_bf16 v[46:49], v[166:169], v[198:201], v[46:49]
	v_mfma_f32_16x16x32_bf16 v[38:41], v[158:161], v[206:209], v[38:41]
	v_mfma_f32_16x16x32_bf16 v[30:33], v[166:169], v[206:209], v[30:33]
	v_mfma_f32_16x16x32_bf16 v[22:25], v[158:161], v[214:217], v[22:25]
	v_mfma_f32_16x16x32_bf16 v[14:17], v[166:169], v[214:217], v[14:17]
	s_setprio 0
	s_setprio 1
	v_mfma_f32_16x16x32_bf16 v[50:53], v[170:173], v[186:189], v[50:53]
	v_mfma_f32_16x16x32_bf16 v[42:45], v[178:181], v[186:189], v[42:45]
	v_mfma_f32_16x16x32_bf16 v[34:37], v[170:173], v[194:197], v[34:37]
	v_mfma_f32_16x16x32_bf16 v[26:29], v[178:181], v[194:197], v[26:29]
	v_mfma_f32_16x16x32_bf16 v[18:21], v[170:173], v[202:205], v[18:21]
	v_mfma_f32_16x16x32_bf16 v[10:13], v[178:181], v[202:205], v[10:13]
	v_mfma_f32_16x16x32_bf16 v[6:9], v[170:173], v[210:213], v[6:9]
	v_mfma_f32_16x16x32_bf16 v[2:5], v[178:181], v[210:213], v[2:5]
	v_mfma_f32_16x16x32_bf16 v[50:53], v[174:177], v[190:193], v[50:53]
	v_mfma_f32_16x16x32_bf16 v[42:45], v[182:185], v[190:193], v[42:45]
	v_mfma_f32_16x16x32_bf16 v[34:37], v[174:177], v[198:201], v[34:37]
	v_mfma_f32_16x16x32_bf16 v[26:29], v[182:185], v[198:201], v[26:29]
	v_mfma_f32_16x16x32_bf16 v[18:21], v[174:177], v[206:209], v[18:21]
	v_mfma_f32_16x16x32_bf16 v[10:13], v[182:185], v[206:209], v[10:13]
	v_mfma_f32_16x16x32_bf16 v[6:9], v[174:177], v[214:217], v[6:9]
	v_mfma_f32_16x16x32_bf16 v[2:5], v[182:185], v[214:217], v[2:5]
	s_setprio 0
	s_barrier
	s_add_i32 s66, 0, 0x18000
	v_add_u32_e32 v153, s66, v148
	s_add_i32 s67, 0, 0x1c000
	ds_read_b128 v[154:157], v153
	ds_read_b128 v[158:161], v153 offset:1024
	ds_read_b128 v[162:165], v153 offset:2048
	ds_read_b128 v[166:169], v153 offset:3072
	v_add_u32_e32 v153, s67, v148
	ds_read_b128 v[170:173], v153
	ds_read_b128 v[174:177], v153 offset:1024
	ds_read_b128 v[178:181], v153 offset:2048
	ds_read_b128 v[182:185], v153 offset:3072
	s_add_u32 s36, s36, 0x40000
	s_addc_u32 s37, s37, 0
	s_mov_b32 m0, s43
	v_lshl_add_u64 v[224:225], s[36:37], 0, v[130:131]
	ds_read_b128 v[186:189], v152 offset:32768
	ds_read_b128 v[190:193], v152 offset:33792
	ds_read_b128 v[194:197], v152 offset:34816
	ds_read_b128 v[198:201], v152 offset:35840
	ds_read_b128 v[202:205], v152 offset:36864
	ds_read_b128 v[206:209], v152 offset:37888
	ds_read_b128 v[210:213], v152 offset:38912
	ds_read_b128 v[214:217], v152 offset:39936
	global_load_lds_dwordx4 v[224:225], off
	v_lshl_add_u64 v[224:225], s[36:37], 0, v[134:135]
	s_mov_b32 m0, s44
	s_nop 0
	global_load_lds_dwordx4 v[224:225], off
	s_waitcnt vmcnt(8)
	s_waitcnt lgkmcnt(0)
	s_barrier
	s_setprio 1
	s_waitcnt lgkmcnt(0)
	v_mfma_f32_16x16x32_bf16 v[126:129], v[154:157], v[186:189], v[126:129]
	v_mfma_f32_16x16x32_bf16 v[122:125], v[162:165], v[186:189], v[122:125]
	v_mfma_f32_16x16x32_bf16 v[118:121], v[154:157], v[194:197], v[118:121]
	v_mfma_f32_16x16x32_bf16 v[110:113], v[162:165], v[194:197], v[110:113]
	v_mfma_f32_16x16x32_bf16 v[102:105], v[154:157], v[202:205], v[102:105]
	v_mfma_f32_16x16x32_bf16 v[94:97], v[162:165], v[202:205], v[94:97]
	v_mfma_f32_16x16x32_bf16 v[86:89], v[154:157], v[210:213], v[86:89]
	v_mfma_f32_16x16x32_bf16 v[78:81], v[162:165], v[210:213], v[78:81]
	v_mfma_f32_16x16x32_bf16 v[126:129], v[158:161], v[190:193], v[126:129]
	v_mfma_f32_16x16x32_bf16 v[122:125], v[166:169], v[190:193], v[122:125]
	v_mfma_f32_16x16x32_bf16 v[118:121], v[158:161], v[198:201], v[118:121]
	v_mfma_f32_16x16x32_bf16 v[110:113], v[166:169], v[198:201], v[110:113]
	v_mfma_f32_16x16x32_bf16 v[102:105], v[158:161], v[206:209], v[102:105]
	v_mfma_f32_16x16x32_bf16 v[94:97], v[166:169], v[206:209], v[94:97]
	v_mfma_f32_16x16x32_bf16 v[86:89], v[158:161], v[214:217], v[86:89]
	v_mfma_f32_16x16x32_bf16 v[78:81], v[166:169], v[214:217], v[78:81]
	s_setprio 0
	s_setprio 1
	v_mfma_f32_16x16x32_bf16 v[114:117], v[170:173], v[186:189], v[114:117]
	v_mfma_f32_16x16x32_bf16 v[106:109], v[178:181], v[186:189], v[106:109]
	v_mfma_f32_16x16x32_bf16 v[98:101], v[170:173], v[194:197], v[98:101]
	v_mfma_f32_16x16x32_bf16 v[90:93], v[178:181], v[194:197], v[90:93]
	v_mfma_f32_16x16x32_bf16 v[82:85], v[170:173], v[202:205], v[82:85]
	v_mfma_f32_16x16x32_bf16 v[74:77], v[178:181], v[202:205], v[74:77]
	v_mfma_f32_16x16x32_bf16 v[70:73], v[170:173], v[210:213], v[70:73]
	v_mfma_f32_16x16x32_bf16 v[66:69], v[178:181], v[210:213], v[66:69]
	v_mfma_f32_16x16x32_bf16 v[114:117], v[174:177], v[190:193], v[114:117]
	v_mfma_f32_16x16x32_bf16 v[106:109], v[182:185], v[190:193], v[106:109]
	v_mfma_f32_16x16x32_bf16 v[98:101], v[174:177], v[198:201], v[98:101]
	v_mfma_f32_16x16x32_bf16 v[90:93], v[182:185], v[198:201], v[90:93]
	v_mfma_f32_16x16x32_bf16 v[82:85], v[174:177], v[206:209], v[82:85]
	v_mfma_f32_16x16x32_bf16 v[74:77], v[182:185], v[206:209], v[74:77]
	v_mfma_f32_16x16x32_bf16 v[70:73], v[174:177], v[214:217], v[70:73]
	v_mfma_f32_16x16x32_bf16 v[66:69], v[182:185], v[214:217], v[66:69]
	s_setprio 0
	s_barrier
	s_add_i32 s36, s66, s41
	v_lshl_add_u64 v[146:147], v[146:147], 0, s[10:11]
	s_mov_b32 m0, s36
	ds_read_b128 v[186:189], v152 offset:49152
	ds_read_b128 v[190:193], v152 offset:50176
	ds_read_b128 v[194:197], v152 offset:51200
	ds_read_b128 v[198:201], v152 offset:52224
	ds_read_b128 v[202:205], v152 offset:53248
	ds_read_b128 v[206:209], v152 offset:54272
	ds_read_b128 v[210:213], v152 offset:55296
	ds_read_b128 v[214:217], v152 offset:56320
	global_load_lds_dwordx4 v[146:147], off
	s_add_i32 m0, s36, 0x2000
	s_add_u32 s34, s34, 0x40080
	v_lshl_add_u64 v[146:147], v[218:219], 0, s[10:11]
	s_addc_u32 s35, s35, 0
	s_add_i32 s36, s67, s41
	global_load_lds_dwordx4 v[146:147], off
	v_lshl_add_u64 v[146:147], s[34:35], 0, v[132:133]
	s_mov_b32 m0, s36
	s_nop 0
	global_load_lds_dwordx4 v[146:147], off
	v_lshl_add_u64 v[146:147], s[34:35], 0, v[136:137]
	s_add_i32 m0, s36, 0x2000
	s_nop 0
	global_load_lds_dwordx4 v[146:147], off
	v_lshl_add_u64 v[146:147], v[220:221], 0, s[10:11]
	s_mov_b32 m0, s46
	s_nop 0
	global_load_lds_dwordx4 v[146:147], off
	v_lshl_add_u64 v[146:147], v[222:223], 0, s[10:11]
	s_mov_b32 m0, s47
	s_nop 0
	global_load_lds_dwordx4 v[146:147], off
	s_waitcnt vmcnt(8)
	s_waitcnt lgkmcnt(0)
	s_barrier
	s_add_i32 s65, s65, 2
	s_add_u32 s30, s30, 0x100
	s_addc_u32 s31, s31, 0
	s_add_u32 s63, s63, 0x100
	s_addc_u32 s64, s64, 0
	s_cmp_gt_u32 s65, 13
	s_setprio 1
	s_waitcnt lgkmcnt(0)
	v_mfma_f32_16x16x32_bf16 v[62:65], v[154:157], v[186:189], v[62:65]
	v_mfma_f32_16x16x32_bf16 v[58:61], v[162:165], v[186:189], v[58:61]
	v_mfma_f32_16x16x32_bf16 v[54:57], v[154:157], v[194:197], v[54:57]
	v_mfma_f32_16x16x32_bf16 v[46:49], v[162:165], v[194:197], v[46:49]
	v_mfma_f32_16x16x32_bf16 v[38:41], v[154:157], v[202:205], v[38:41]
	v_mfma_f32_16x16x32_bf16 v[30:33], v[162:165], v[202:205], v[30:33]
	v_mfma_f32_16x16x32_bf16 v[22:25], v[154:157], v[210:213], v[22:25]
	v_mfma_f32_16x16x32_bf16 v[14:17], v[162:165], v[210:213], v[14:17]
	v_mfma_f32_16x16x32_bf16 v[62:65], v[158:161], v[190:193], v[62:65]
	v_mfma_f32_16x16x32_bf16 v[58:61], v[166:169], v[190:193], v[58:61]
	v_mfma_f32_16x16x32_bf16 v[54:57], v[158:161], v[198:201], v[54:57]
	v_mfma_f32_16x16x32_bf16 v[46:49], v[166:169], v[198:201], v[46:49]
	v_mfma_f32_16x16x32_bf16 v[38:41], v[158:161], v[206:209], v[38:41]
	v_mfma_f32_16x16x32_bf16 v[30:33], v[166:169], v[206:209], v[30:33]
	v_mfma_f32_16x16x32_bf16 v[22:25], v[158:161], v[214:217], v[22:25]
	v_mfma_f32_16x16x32_bf16 v[14:17], v[166:169], v[214:217], v[14:17]
	s_setprio 0
	s_setprio 1
	v_mfma_f32_16x16x32_bf16 v[50:53], v[170:173], v[186:189], v[50:53]
	v_mfma_f32_16x16x32_bf16 v[42:45], v[178:181], v[186:189], v[42:45]
	v_mfma_f32_16x16x32_bf16 v[34:37], v[170:173], v[194:197], v[34:37]
	v_mfma_f32_16x16x32_bf16 v[26:29], v[178:181], v[194:197], v[26:29]
	v_mfma_f32_16x16x32_bf16 v[18:21], v[170:173], v[202:205], v[18:21]
	v_mfma_f32_16x16x32_bf16 v[10:13], v[178:181], v[202:205], v[10:13]
	v_mfma_f32_16x16x32_bf16 v[6:9], v[170:173], v[210:213], v[6:9]
	v_mfma_f32_16x16x32_bf16 v[2:5], v[178:181], v[210:213], v[2:5]
	v_mfma_f32_16x16x32_bf16 v[50:53], v[174:177], v[190:193], v[50:53]
	v_mfma_f32_16x16x32_bf16 v[42:45], v[182:185], v[190:193], v[42:45]
	v_mfma_f32_16x16x32_bf16 v[34:37], v[174:177], v[198:201], v[34:37]
	v_mfma_f32_16x16x32_bf16 v[26:29], v[182:185], v[198:201], v[26:29]
	v_mfma_f32_16x16x32_bf16 v[18:21], v[174:177], v[206:209], v[18:21]
	v_mfma_f32_16x16x32_bf16 v[10:13], v[182:185], v[206:209], v[10:13]
	v_mfma_f32_16x16x32_bf16 v[6:9], v[174:177], v[214:217], v[6:9]
	v_mfma_f32_16x16x32_bf16 v[2:5], v[182:185], v[214:217], v[2:5]
	s_setprio 0
	s_barrier
	s_cbranch_scc0 .LBB0_1031
	s_and_b64 vcc, exec, s[12:13]
	s_cbranch_vccz .LBB0_1034
	s_barrier

.LBB0_1166:
	ds_read_b128 v[154:157], v150
	ds_read_b128 v[158:161], v150 offset:1024
	ds_read_b128 v[162:165], v150 offset:2048
	ds_read_b128 v[166:169], v150 offset:3072
	ds_read_b128 v[170:173], v151
	ds_read_b128 v[174:177], v151 offset:1024
	ds_read_b128 v[178:181], v151 offset:2048
	ds_read_b128 v[182:185], v151 offset:3072
	s_add_u32 s34, s30, 0xfffc0080
	s_addc_u32 s35, s31, -1
	s_cmp_eq_u32 s65, 12
	s_cselect_b32 s37, s23, s35
	s_cselect_b32 s36, s61, s34
	s_cselect_b32 s35, s21, s64
	s_cselect_b32 s34, s62, s63
	v_lshl_add_u64 v[146:147], s[30:31], 0, v[138:139]
	s_add_i32 m0, s29, 0xc000
	ds_read_b128 v[186:189], v152
	ds_read_b128 v[190:193], v152 offset:1024
	ds_read_b128 v[194:197], v152 offset:2048
	ds_read_b128 v[198:201], v152 offset:3072
	ds_read_b128 v[202:205], v152 offset:4096
	ds_read_b128 v[206:209], v152 offset:5120
	ds_read_b128 v[210:213], v152 offset:6144
	ds_read_b128 v[214:217], v152 offset:7168
	global_load_lds_dwordx4 v[146:147], off
	v_lshl_add_u64 v[146:147], s[30:31], 0, v[140:141]
	s_add_i32 m0, s29, 0xe000
	s_nop 0
	global_load_lds_dwordx4 v[146:147], off
	s_waitcnt vmcnt(8)
	s_waitcnt lgkmcnt(0)
	s_barrier
	s_setprio 1
	s_waitcnt lgkmcnt(0)
	v_mfma_f32_16x16x32_bf16 v[126:129], v[154:157], v[186:189], v[126:129]
	v_mfma_f32_16x16x32_bf16 v[122:125], v[162:165], v[186:189], v[122:125]
	v_mfma_f32_16x16x32_bf16 v[110:113], v[154:157], v[194:197], v[110:113]
	v_mfma_f32_16x16x32_bf16 v[106:109], v[162:165], v[194:197], v[106:109]
	v_mfma_f32_16x16x32_bf16 v[94:97], v[154:157], v[202:205], v[94:97]
	v_mfma_f32_16x16x32_bf16 v[90:93], v[162:165], v[202:205], v[90:93]
	v_mfma_f32_16x16x32_bf16 v[78:81], v[154:157], v[210:213], v[78:81]
	v_mfma_f32_16x16x32_bf16 v[74:77], v[162:165], v[210:213], v[74:77]
	v_mfma_f32_16x16x32_bf16 v[126:129], v[158:161], v[190:193], v[126:129]
	v_mfma_f32_16x16x32_bf16 v[122:125], v[166:169], v[190:193], v[122:125]
	v_mfma_f32_16x16x32_bf16 v[110:113], v[158:161], v[198:201], v[110:113]
	v_mfma_f32_16x16x32_bf16 v[106:109], v[166:169], v[198:201], v[106:109]
	v_mfma_f32_16x16x32_bf16 v[94:97], v[158:161], v[206:209], v[94:97]
	v_mfma_f32_16x16x32_bf16 v[90:93], v[166:169], v[206:209], v[90:93]
	v_mfma_f32_16x16x32_bf16 v[78:81], v[158:161], v[214:217], v[78:81]
	v_mfma_f32_16x16x32_bf16 v[74:77], v[166:169], v[214:217], v[74:77]
	s_setprio 0
	s_setprio 1
	v_mfma_f32_16x16x32_bf16 v[118:121], v[170:173], v[186:189], v[118:121]
	v_mfma_f32_16x16x32_bf16 v[114:117], v[178:181], v[186:189], v[114:117]
	v_mfma_f32_16x16x32_bf16 v[102:105], v[170:173], v[194:197], v[102:105]
	v_mfma_f32_16x16x32_bf16 v[98:101], v[178:181], v[194:197], v[98:101]
	v_mfma_f32_16x16x32_bf16 v[86:89], v[170:173], v[202:205], v[86:89]
	v_mfma_f32_16x16x32_bf16 v[82:85], v[178:181], v[202:205], v[82:85]
	v_mfma_f32_16x16x32_bf16 v[70:73], v[170:173], v[210:213], v[70:73]
	v_mfma_f32_16x16x32_bf16 v[66:69], v[178:181], v[210:213], v[66:69]
	v_mfma_f32_16x16x32_bf16 v[118:121], v[174:177], v[190:193], v[118:121]
	v_mfma_f32_16x16x32_bf16 v[114:117], v[182:185], v[190:193], v[114:117]
	v_mfma_f32_16x16x32_bf16 v[102:105], v[174:177], v[198:201], v[102:105]
	v_mfma_f32_16x16x32_bf16 v[98:101], v[182:185], v[198:201], v[98:101]
	v_mfma_f32_16x16x32_bf16 v[86:89], v[174:177], v[206:209], v[86:89]
	v_mfma_f32_16x16x32_bf16 v[82:85], v[182:185], v[206:209], v[82:85]
	v_mfma_f32_16x16x32_bf16 v[70:73], v[174:177], v[214:217], v[70:73]
	v_mfma_f32_16x16x32_bf16 v[66:69], v[182:185], v[214:217], v[66:69]
	s_setprio 0
	s_barrier
	s_add_i32 s66, s54, s41
	v_lshl_add_u64 v[146:147], s[34:35], 0, v[132:133]
	s_mov_b32 m0, s66
	ds_read_b128 v[186:189], v152 offset:16384
	ds_read_b128 v[190:193], v152 offset:17408
	ds_read_b128 v[194:197], v152 offset:18432
	ds_read_b128 v[198:201], v152 offset:19456
	ds_read_b128 v[202:205], v152 offset:20480
	ds_read_b128 v[206:209], v152 offset:21504
	ds_read_b128 v[210:213], v152 offset:22528
	ds_read_b128 v[214:217], v152 offset:23552
	global_load_lds_dwordx4 v[146:147], off
	s_add_i32 m0, s66, 0x2000
	s_add_u32 s66, s34, 0x40000
	v_lshl_add_u64 v[218:219], s[34:35], 0, v[136:137]
	s_addc_u32 s67, s35, 0
	s_add_i32 s68, s55, s41
	global_load_lds_dwordx4 v[218:219], off
	v_lshl_add_u64 v[220:221], s[66:67], 0, v[132:133]
	s_mov_b32 m0, s68
	v_lshl_add_u64 v[222:223], s[36:37], 0, v[134:135]
	global_load_lds_dwordx4 v[220:221], off
	v_lshl_add_u64 v[220:221], s[66:67], 0, v[136:137]
	s_add_i32 m0, s68, 0x2000
	s_nop 0
	global_load_lds_dwordx4 v[220:221], off
	v_lshl_add_u64 v[220:221], s[36:37], 0, v[130:131]
	s_mov_b32 m0, s29
	s_nop 0
	global_load_lds_dwordx4 v[220:221], off
	s_mov_b32 m0, s42
	s_nop 0
	global_load_lds_dwordx4 v[222:223], off
	s_waitcnt vmcnt(8)
	s_waitcnt lgkmcnt(0)
	s_barrier
	s_setprio 1
	s_waitcnt lgkmcnt(0)
	v_mfma_f32_16x16x32_bf16 v[62:65], v[154:157], v[186:189], v[62:65]
	v_mfma_f32_16x16x32_bf16 v[58:61], v[162:165], v[186:189], v[58:61]
	v_mfma_f32_16x16x32_bf16 v[46:49], v[154:157], v[194:197], v[46:49]
	v_mfma_f32_16x16x32_bf16 v[42:45], v[162:165], v[194:197], v[42:45]
	v_mfma_f32_16x16x32_bf16 v[30:33], v[154:157], v[202:205], v[30:33]
	v_mfma_f32_16x16x32_bf16 v[26:29], v[162:165], v[202:205], v[26:29]
	v_mfma_f32_16x16x32_bf16 v[14:17], v[154:157], v[210:213], v[14:17]
	v_mfma_f32_16x16x32_bf16 v[10:13], v[162:165], v[210:213], v[10:13]
	v_mfma_f32_16x16x32_bf16 v[62:65], v[158:161], v[190:193], v[62:65]
	v_mfma_f32_16x16x32_bf16 v[58:61], v[166:169], v[190:193], v[58:61]
	v_mfma_f32_16x16x32_bf16 v[46:49], v[158:161], v[198:201], v[46:49]
	v_mfma_f32_16x16x32_bf16 v[42:45], v[166:169], v[198:201], v[42:45]
	v_mfma_f32_16x16x32_bf16 v[30:33], v[158:161], v[206:209], v[30:33]
	v_mfma_f32_16x16x32_bf16 v[26:29], v[166:169], v[206:209], v[26:29]
	v_mfma_f32_16x16x32_bf16 v[14:17], v[158:161], v[214:217], v[14:17]
	v_mfma_f32_16x16x32_bf16 v[10:13], v[166:169], v[214:217], v[10:13]
	s_setprio 0
	s_setprio 1
	v_mfma_f32_16x16x32_bf16 v[54:57], v[170:173], v[186:189], v[54:57]
	v_mfma_f32_16x16x32_bf16 v[50:53], v[178:181], v[186:189], v[50:53]
	v_mfma_f32_16x16x32_bf16 v[38:41], v[170:173], v[194:197], v[38:41]
	v_mfma_f32_16x16x32_bf16 v[34:37], v[178:181], v[194:197], v[34:37]
	v_mfma_f32_16x16x32_bf16 v[22:25], v[170:173], v[202:205], v[22:25]
	v_mfma_f32_16x16x32_bf16 v[18:21], v[178:181], v[202:205], v[18:21]
	v_mfma_f32_16x16x32_bf16 v[6:9], v[170:173], v[210:213], v[6:9]
	v_mfma_f32_16x16x32_bf16 v[2:5], v[178:181], v[210:213], v[2:5]
	v_mfma_f32_16x16x32_bf16 v[54:57], v[174:177], v[190:193], v[54:57]
	v_mfma_f32_16x16x32_bf16 v[50:53], v[182:185], v[190:193], v[50:53]
	v_mfma_f32_16x16x32_bf16 v[38:41], v[174:177], v[198:201], v[38:41]
	v_mfma_f32_16x16x32_bf16 v[34:37], v[182:185], v[198:201], v[34:37]
	v_mfma_f32_16x16x32_bf16 v[22:25], v[174:177], v[206:209], v[22:25]
	v_mfma_f32_16x16x32_bf16 v[18:21], v[182:185], v[206:209], v[18:21]
	v_mfma_f32_16x16x32_bf16 v[6:9], v[174:177], v[214:217], v[6:9]
	v_mfma_f32_16x16x32_bf16 v[2:5], v[182:185], v[214:217], v[2:5]
	s_setprio 0
	s_barrier
	s_add_i32 s66, 0, 0x18000
	v_add_u32_e32 v153, s66, v148
	s_add_i32 s67, 0, 0x1c000
	ds_read_b128 v[154:157], v153
	ds_read_b128 v[158:161], v153 offset:1024
	ds_read_b128 v[162:165], v153 offset:2048
	ds_read_b128 v[166:169], v153 offset:3072
	v_add_u32_e32 v153, s67, v148
	ds_read_b128 v[170:173], v153
	ds_read_b128 v[174:177], v153 offset:1024
	ds_read_b128 v[178:181], v153 offset:2048
	ds_read_b128 v[182:185], v153 offset:3072
	s_add_u32 s36, s36, 0x40000
	s_addc_u32 s37, s37, 0
	s_mov_b32 m0, s43
	v_lshl_add_u64 v[224:225], s[36:37], 0, v[130:131]
	ds_read_b128 v[186:189], v152 offset:32768
	ds_read_b128 v[190:193], v152 offset:33792
	ds_read_b128 v[194:197], v152 offset:34816
	ds_read_b128 v[198:201], v152 offset:35840
	ds_read_b128 v[202:205], v152 offset:36864
	ds_read_b128 v[206:209], v152 offset:37888
	ds_read_b128 v[210:213], v152 offset:38912
	ds_read_b128 v[214:217], v152 offset:39936
	global_load_lds_dwordx4 v[224:225], off
	v_lshl_add_u64 v[224:225], s[36:37], 0, v[134:135]
	s_mov_b32 m0, s44
	s_nop 0
	global_load_lds_dwordx4 v[224:225], off
	s_waitcnt vmcnt(8)
	s_waitcnt lgkmcnt(0)
	s_barrier
	s_setprio 1
	s_waitcnt lgkmcnt(0)
	v_mfma_f32_16x16x32_bf16 v[126:129], v[154:157], v[186:189], v[126:129]
	v_mfma_f32_16x16x32_bf16 v[122:125], v[162:165], v[186:189], v[122:125]
	v_mfma_f32_16x16x32_bf16 v[110:113], v[154:157], v[194:197], v[110:113]
	v_mfma_f32_16x16x32_bf16 v[106:109], v[162:165], v[194:197], v[106:109]
	v_mfma_f32_16x16x32_bf16 v[94:97], v[154:157], v[202:205], v[94:97]
	v_mfma_f32_16x16x32_bf16 v[90:93], v[162:165], v[202:205], v[90:93]
	v_mfma_f32_16x16x32_bf16 v[78:81], v[154:157], v[210:213], v[78:81]
	v_mfma_f32_16x16x32_bf16 v[74:77], v[162:165], v[210:213], v[74:77]
	v_mfma_f32_16x16x32_bf16 v[126:129], v[158:161], v[190:193], v[126:129]
	v_mfma_f32_16x16x32_bf16 v[122:125], v[166:169], v[190:193], v[122:125]
	v_mfma_f32_16x16x32_bf16 v[110:113], v[158:161], v[198:201], v[110:113]
	v_mfma_f32_16x16x32_bf16 v[106:109], v[166:169], v[198:201], v[106:109]
	v_mfma_f32_16x16x32_bf16 v[94:97], v[158:161], v[206:209], v[94:97]
	v_mfma_f32_16x16x32_bf16 v[90:93], v[166:169], v[206:209], v[90:93]
	v_mfma_f32_16x16x32_bf16 v[78:81], v[158:161], v[214:217], v[78:81]
	v_mfma_f32_16x16x32_bf16 v[74:77], v[166:169], v[214:217], v[74:77]
	s_setprio 0
	s_setprio 1
	v_mfma_f32_16x16x32_bf16 v[118:121], v[170:173], v[186:189], v[118:121]
	v_mfma_f32_16x16x32_bf16 v[114:117], v[178:181], v[186:189], v[114:117]
	v_mfma_f32_16x16x32_bf16 v[102:105], v[170:173], v[194:197], v[102:105]
	v_mfma_f32_16x16x32_bf16 v[98:101], v[178:181], v[194:197], v[98:101]
	v_mfma_f32_16x16x32_bf16 v[86:89], v[170:173], v[202:205], v[86:89]
	v_mfma_f32_16x16x32_bf16 v[82:85], v[178:181], v[202:205], v[82:85]
	v_mfma_f32_16x16x32_bf16 v[70:73], v[170:173], v[210:213], v[70:73]
	v_mfma_f32_16x16x32_bf16 v[66:69], v[178:181], v[210:213], v[66:69]
	v_mfma_f32_16x16x32_bf16 v[118:121], v[174:177], v[190:193], v[118:121]
	v_mfma_f32_16x16x32_bf16 v[114:117], v[182:185], v[190:193], v[114:117]
	v_mfma_f32_16x16x32_bf16 v[102:105], v[174:177], v[198:201], v[102:105]
	v_mfma_f32_16x16x32_bf16 v[98:101], v[182:185], v[198:201], v[98:101]
	v_mfma_f32_16x16x32_bf16 v[86:89], v[174:177], v[206:209], v[86:89]
	v_mfma_f32_16x16x32_bf16 v[82:85], v[182:185], v[206:209], v[82:85]
	v_mfma_f32_16x16x32_bf16 v[70:73], v[174:177], v[214:217], v[70:73]
	v_mfma_f32_16x16x32_bf16 v[66:69], v[182:185], v[214:217], v[66:69]
	s_setprio 0
	s_barrier
	s_add_i32 s36, s66, s41
	v_lshl_add_u64 v[146:147], v[146:147], 0, s[8:9]
	s_mov_b32 m0, s36
	ds_read_b128 v[186:189], v152 offset:49152
	ds_read_b128 v[190:193], v152 offset:50176
	ds_read_b128 v[194:197], v152 offset:51200
	ds_read_b128 v[198:201], v152 offset:52224
	ds_read_b128 v[202:205], v152 offset:53248
	ds_read_b128 v[206:209], v152 offset:54272
	ds_read_b128 v[210:213], v152 offset:55296
	ds_read_b128 v[214:217], v152 offset:56320
	global_load_lds_dwordx4 v[146:147], off
	s_add_i32 m0, s36, 0x2000
	s_add_u32 s34, s34, 0x40080
	v_lshl_add_u64 v[146:147], v[218:219], 0, s[8:9]
	s_addc_u32 s35, s35, 0
	s_add_i32 s36, s67, s41
	global_load_lds_dwordx4 v[146:147], off
	v_lshl_add_u64 v[146:147], s[34:35], 0, v[132:133]
	s_mov_b32 m0, s36
	s_nop 0
	global_load_lds_dwordx4 v[146:147], off
	v_lshl_add_u64 v[146:147], s[34:35], 0, v[136:137]
	s_add_i32 m0, s36, 0x2000
	s_nop 0
	global_load_lds_dwordx4 v[146:147], off
	v_lshl_add_u64 v[146:147], v[220:221], 0, s[8:9]
	s_mov_b32 m0, s46
	s_nop 0
	global_load_lds_dwordx4 v[146:147], off
	v_lshl_add_u64 v[146:147], v[222:223], 0, s[8:9]
	s_mov_b32 m0, s47
	s_nop 0
	global_load_lds_dwordx4 v[146:147], off
	s_waitcnt vmcnt(8)
	s_waitcnt lgkmcnt(0)
	s_barrier
	s_add_i32 s65, s65, 2
	s_add_u32 s30, s30, 0x100
	s_addc_u32 s31, s31, 0
	s_add_u32 s63, s63, 0x100
	s_addc_u32 s64, s64, 0
	s_cmp_gt_u32 s65, 13
	s_setprio 1
	s_waitcnt lgkmcnt(0)
	v_mfma_f32_16x16x32_bf16 v[62:65], v[154:157], v[186:189], v[62:65]
	v_mfma_f32_16x16x32_bf16 v[58:61], v[162:165], v[186:189], v[58:61]
	v_mfma_f32_16x16x32_bf16 v[46:49], v[154:157], v[194:197], v[46:49]
	v_mfma_f32_16x16x32_bf16 v[42:45], v[162:165], v[194:197], v[42:45]
	v_mfma_f32_16x16x32_bf16 v[30:33], v[154:157], v[202:205], v[30:33]
	v_mfma_f32_16x16x32_bf16 v[26:29], v[162:165], v[202:205], v[26:29]
	v_mfma_f32_16x16x32_bf16 v[14:17], v[154:157], v[210:213], v[14:17]
	v_mfma_f32_16x16x32_bf16 v[10:13], v[162:165], v[210:213], v[10:13]
	v_mfma_f32_16x16x32_bf16 v[62:65], v[158:161], v[190:193], v[62:65]
	v_mfma_f32_16x16x32_bf16 v[58:61], v[166:169], v[190:193], v[58:61]
	v_mfma_f32_16x16x32_bf16 v[46:49], v[158:161], v[198:201], v[46:49]
	v_mfma_f32_16x16x32_bf16 v[42:45], v[166:169], v[198:201], v[42:45]
	v_mfma_f32_16x16x32_bf16 v[30:33], v[158:161], v[206:209], v[30:33]
	v_mfma_f32_16x16x32_bf16 v[26:29], v[166:169], v[206:209], v[26:29]
	v_mfma_f32_16x16x32_bf16 v[14:17], v[158:161], v[214:217], v[14:17]
	v_mfma_f32_16x16x32_bf16 v[10:13], v[166:169], v[214:217], v[10:13]
	s_setprio 0
	s_setprio 1
	v_mfma_f32_16x16x32_bf16 v[54:57], v[170:173], v[186:189], v[54:57]
	v_mfma_f32_16x16x32_bf16 v[50:53], v[178:181], v[186:189], v[50:53]
	v_mfma_f32_16x16x32_bf16 v[38:41], v[170:173], v[194:197], v[38:41]
	v_mfma_f32_16x16x32_bf16 v[34:37], v[178:181], v[194:197], v[34:37]
	v_mfma_f32_16x16x32_bf16 v[22:25], v[170:173], v[202:205], v[22:25]
	v_mfma_f32_16x16x32_bf16 v[18:21], v[178:181], v[202:205], v[18:21]
	v_mfma_f32_16x16x32_bf16 v[6:9], v[170:173], v[210:213], v[6:9]
	v_mfma_f32_16x16x32_bf16 v[2:5], v[178:181], v[210:213], v[2:5]
	v_mfma_f32_16x16x32_bf16 v[54:57], v[174:177], v[190:193], v[54:57]
	v_mfma_f32_16x16x32_bf16 v[50:53], v[182:185], v[190:193], v[50:53]
	v_mfma_f32_16x16x32_bf16 v[38:41], v[174:177], v[198:201], v[38:41]
	v_mfma_f32_16x16x32_bf16 v[34:37], v[182:185], v[198:201], v[34:37]
	v_mfma_f32_16x16x32_bf16 v[22:25], v[174:177], v[206:209], v[22:25]
	v_mfma_f32_16x16x32_bf16 v[18:21], v[182:185], v[206:209], v[18:21]
	v_mfma_f32_16x16x32_bf16 v[6:9], v[174:177], v[214:217], v[6:9]
	v_mfma_f32_16x16x32_bf16 v[2:5], v[182:185], v[214:217], v[2:5]
	s_setprio 0
	s_barrier
	s_cbranch_scc0 .LBB0_1166
	s_and_b64 vcc, exec, s[10:11]
	s_cbranch_vccz .LBB0_1169
	s_barrier

.LBB0_1241:
	ds_read_b128 v[154:157], v150
	ds_read_b128 v[158:161], v150 offset:1024
	ds_read_b128 v[162:165], v150 offset:2048
	ds_read_b128 v[166:169], v150 offset:3072
	ds_read_b128 v[170:173], v151
	ds_read_b128 v[174:177], v151 offset:1024
	ds_read_b128 v[178:181], v151 offset:2048
	ds_read_b128 v[182:185], v151 offset:3072
	s_add_u32 s34, s30, 0xfff00080
	s_addc_u32 s35, s31, -1
	s_cmp_eq_u32 s65, 60
	s_cselect_b32 s37, s23, s35
	s_cselect_b32 s36, s61, s34
	s_cselect_b32 s35, s21, s64
	s_cselect_b32 s34, s62, s63
	v_lshl_add_u64 v[146:147], s[30:31], 0, v[138:139]
	s_add_i32 m0, s29, 0xc000
	ds_read_b128 v[186:189], v152
	ds_read_b128 v[190:193], v152 offset:1024
	ds_read_b128 v[194:197], v152 offset:2048
	ds_read_b128 v[198:201], v152 offset:3072
	ds_read_b128 v[202:205], v152 offset:4096
	ds_read_b128 v[206:209], v152 offset:5120
	ds_read_b128 v[210:213], v152 offset:6144
	ds_read_b128 v[214:217], v152 offset:7168
	global_load_lds_dwordx4 v[146:147], off
	v_lshl_add_u64 v[146:147], s[30:31], 0, v[140:141]
	s_add_i32 m0, s29, 0xe000
	s_nop 0
	global_load_lds_dwordx4 v[146:147], off
	s_waitcnt vmcnt(8)
	s_waitcnt lgkmcnt(0)
	s_barrier
	s_setprio 1
	s_waitcnt lgkmcnt(0)
	v_mfma_f32_16x16x32_bf16 v[126:129], v[154:157], v[186:189], v[126:129]
	v_mfma_f32_16x16x32_bf16 v[122:125], v[162:165], v[186:189], v[122:125]
	v_mfma_f32_16x16x32_bf16 v[118:121], v[154:157], v[194:197], v[118:121]
	v_mfma_f32_16x16x32_bf16 v[110:113], v[162:165], v[194:197], v[110:113]
	v_mfma_f32_16x16x32_bf16 v[102:105], v[154:157], v[202:205], v[102:105]
	v_mfma_f32_16x16x32_bf16 v[94:97], v[162:165], v[202:205], v[94:97]
	v_mfma_f32_16x16x32_bf16 v[86:89], v[154:157], v[210:213], v[86:89]
	v_mfma_f32_16x16x32_bf16 v[78:81], v[162:165], v[210:213], v[78:81]
	v_mfma_f32_16x16x32_bf16 v[126:129], v[158:161], v[190:193], v[126:129]
	v_mfma_f32_16x16x32_bf16 v[122:125], v[166:169], v[190:193], v[122:125]
	v_mfma_f32_16x16x32_bf16 v[118:121], v[158:161], v[198:201], v[118:121]
	v_mfma_f32_16x16x32_bf16 v[110:113], v[166:169], v[198:201], v[110:113]
	v_mfma_f32_16x16x32_bf16 v[102:105], v[158:161], v[206:209], v[102:105]
	v_mfma_f32_16x16x32_bf16 v[94:97], v[166:169], v[206:209], v[94:97]
	v_mfma_f32_16x16x32_bf16 v[86:89], v[158:161], v[214:217], v[86:89]
	v_mfma_f32_16x16x32_bf16 v[78:81], v[166:169], v[214:217], v[78:81]
	s_setprio 0
	s_setprio 1
	v_mfma_f32_16x16x32_bf16 v[114:117], v[170:173], v[186:189], v[114:117]
	v_mfma_f32_16x16x32_bf16 v[106:109], v[178:181], v[186:189], v[106:109]
	v_mfma_f32_16x16x32_bf16 v[98:101], v[170:173], v[194:197], v[98:101]
	v_mfma_f32_16x16x32_bf16 v[90:93], v[178:181], v[194:197], v[90:93]
	v_mfma_f32_16x16x32_bf16 v[82:85], v[170:173], v[202:205], v[82:85]
	v_mfma_f32_16x16x32_bf16 v[74:77], v[178:181], v[202:205], v[74:77]
	v_mfma_f32_16x16x32_bf16 v[70:73], v[170:173], v[210:213], v[70:73]
	v_mfma_f32_16x16x32_bf16 v[66:69], v[178:181], v[210:213], v[66:69]
	v_mfma_f32_16x16x32_bf16 v[114:117], v[174:177], v[190:193], v[114:117]
	v_mfma_f32_16x16x32_bf16 v[106:109], v[182:185], v[190:193], v[106:109]
	v_mfma_f32_16x16x32_bf16 v[98:101], v[174:177], v[198:201], v[98:101]
	v_mfma_f32_16x16x32_bf16 v[90:93], v[182:185], v[198:201], v[90:93]
	v_mfma_f32_16x16x32_bf16 v[82:85], v[174:177], v[206:209], v[82:85]
	v_mfma_f32_16x16x32_bf16 v[74:77], v[182:185], v[206:209], v[74:77]
	v_mfma_f32_16x16x32_bf16 v[70:73], v[174:177], v[214:217], v[70:73]
	v_mfma_f32_16x16x32_bf16 v[66:69], v[182:185], v[214:217], v[66:69]
	s_setprio 0
	s_barrier
	s_add_i32 s66, s54, s41
	v_lshl_add_u64 v[146:147], s[34:35], 0, v[132:133]
	s_mov_b32 m0, s66
	ds_read_b128 v[186:189], v152 offset:16384
	ds_read_b128 v[190:193], v152 offset:17408
	ds_read_b128 v[194:197], v152 offset:18432
	ds_read_b128 v[198:201], v152 offset:19456
	ds_read_b128 v[202:205], v152 offset:20480
	ds_read_b128 v[206:209], v152 offset:21504
	ds_read_b128 v[210:213], v152 offset:22528
	ds_read_b128 v[214:217], v152 offset:23552
	global_load_lds_dwordx4 v[146:147], off
	s_add_i32 m0, s66, 0x2000
	s_add_u32 s66, s34, 0x100000
	v_lshl_add_u64 v[218:219], s[34:35], 0, v[136:137]
	s_addc_u32 s67, s35, 0
	s_add_i32 s68, s55, s41
	global_load_lds_dwordx4 v[218:219], off
	v_lshl_add_u64 v[220:221], s[66:67], 0, v[132:133]
	s_mov_b32 m0, s68
	v_lshl_add_u64 v[222:223], s[36:37], 0, v[134:135]
	global_load_lds_dwordx4 v[220:221], off
	v_lshl_add_u64 v[220:221], s[66:67], 0, v[136:137]
	s_add_i32 m0, s68, 0x2000
	s_nop 0
	global_load_lds_dwordx4 v[220:221], off
	v_lshl_add_u64 v[220:221], s[36:37], 0, v[130:131]
	s_mov_b32 m0, s29
	s_nop 0
	global_load_lds_dwordx4 v[220:221], off
	s_mov_b32 m0, s42
	s_nop 0
	global_load_lds_dwordx4 v[222:223], off
	s_waitcnt vmcnt(8)
	s_waitcnt lgkmcnt(0)
	s_barrier
	s_setprio 1
	s_waitcnt lgkmcnt(0)
	v_mfma_f32_16x16x32_bf16 v[62:65], v[154:157], v[186:189], v[62:65]
	v_mfma_f32_16x16x32_bf16 v[58:61], v[162:165], v[186:189], v[58:61]
	v_mfma_f32_16x16x32_bf16 v[54:57], v[154:157], v[194:197], v[54:57]
	v_mfma_f32_16x16x32_bf16 v[46:49], v[162:165], v[194:197], v[46:49]
	v_mfma_f32_16x16x32_bf16 v[38:41], v[154:157], v[202:205], v[38:41]
	v_mfma_f32_16x16x32_bf16 v[30:33], v[162:165], v[202:205], v[30:33]
	v_mfma_f32_16x16x32_bf16 v[22:25], v[154:157], v[210:213], v[22:25]
	v_mfma_f32_16x16x32_bf16 v[14:17], v[162:165], v[210:213], v[14:17]
	v_mfma_f32_16x16x32_bf16 v[62:65], v[158:161], v[190:193], v[62:65]
	v_mfma_f32_16x16x32_bf16 v[58:61], v[166:169], v[190:193], v[58:61]
	v_mfma_f32_16x16x32_bf16 v[54:57], v[158:161], v[198:201], v[54:57]
	v_mfma_f32_16x16x32_bf16 v[46:49], v[166:169], v[198:201], v[46:49]
	v_mfma_f32_16x16x32_bf16 v[38:41], v[158:161], v[206:209], v[38:41]
	v_mfma_f32_16x16x32_bf16 v[30:33], v[166:169], v[206:209], v[30:33]
	v_mfma_f32_16x16x32_bf16 v[22:25], v[158:161], v[214:217], v[22:25]
	v_mfma_f32_16x16x32_bf16 v[14:17], v[166:169], v[214:217], v[14:17]
	s_setprio 0
	s_setprio 1
	v_mfma_f32_16x16x32_bf16 v[50:53], v[170:173], v[186:189], v[50:53]
	v_mfma_f32_16x16x32_bf16 v[42:45], v[178:181], v[186:189], v[42:45]
	v_mfma_f32_16x16x32_bf16 v[34:37], v[170:173], v[194:197], v[34:37]
	v_mfma_f32_16x16x32_bf16 v[26:29], v[178:181], v[194:197], v[26:29]
	v_mfma_f32_16x16x32_bf16 v[18:21], v[170:173], v[202:205], v[18:21]
	v_mfma_f32_16x16x32_bf16 v[10:13], v[178:181], v[202:205], v[10:13]
	v_mfma_f32_16x16x32_bf16 v[6:9], v[170:173], v[210:213], v[6:9]
	v_mfma_f32_16x16x32_bf16 v[2:5], v[178:181], v[210:213], v[2:5]
	v_mfma_f32_16x16x32_bf16 v[50:53], v[174:177], v[190:193], v[50:53]
	v_mfma_f32_16x16x32_bf16 v[42:45], v[182:185], v[190:193], v[42:45]
	v_mfma_f32_16x16x32_bf16 v[34:37], v[174:177], v[198:201], v[34:37]
	v_mfma_f32_16x16x32_bf16 v[26:29], v[182:185], v[198:201], v[26:29]
	v_mfma_f32_16x16x32_bf16 v[18:21], v[174:177], v[206:209], v[18:21]
	v_mfma_f32_16x16x32_bf16 v[10:13], v[182:185], v[206:209], v[10:13]
	v_mfma_f32_16x16x32_bf16 v[6:9], v[174:177], v[214:217], v[6:9]
	v_mfma_f32_16x16x32_bf16 v[2:5], v[182:185], v[214:217], v[2:5]
	s_setprio 0
	s_barrier
	s_add_i32 s66, 0, 0x18000
	v_add_u32_e32 v153, s66, v148
	s_add_i32 s67, 0, 0x1c000
	ds_read_b128 v[154:157], v153
	ds_read_b128 v[158:161], v153 offset:1024
	ds_read_b128 v[162:165], v153 offset:2048
	ds_read_b128 v[166:169], v153 offset:3072
	v_add_u32_e32 v153, s67, v148
	ds_read_b128 v[170:173], v153
	ds_read_b128 v[174:177], v153 offset:1024
	ds_read_b128 v[178:181], v153 offset:2048
	ds_read_b128 v[182:185], v153 offset:3072
	s_add_u32 s36, s36, 0x100000
	s_addc_u32 s37, s37, 0
	s_mov_b32 m0, s43
	v_lshl_add_u64 v[224:225], s[36:37], 0, v[130:131]
	ds_read_b128 v[186:189], v152 offset:32768
	ds_read_b128 v[190:193], v152 offset:33792
	ds_read_b128 v[194:197], v152 offset:34816
	ds_read_b128 v[198:201], v152 offset:35840
	ds_read_b128 v[202:205], v152 offset:36864
	ds_read_b128 v[206:209], v152 offset:37888
	ds_read_b128 v[210:213], v152 offset:38912
	ds_read_b128 v[214:217], v152 offset:39936
	global_load_lds_dwordx4 v[224:225], off
	v_lshl_add_u64 v[224:225], s[36:37], 0, v[134:135]
	s_mov_b32 m0, s44
	s_nop 0
	global_load_lds_dwordx4 v[224:225], off
	s_waitcnt vmcnt(8)
	s_waitcnt lgkmcnt(0)
	s_barrier
	s_setprio 1
	s_waitcnt lgkmcnt(0)
	v_mfma_f32_16x16x32_bf16 v[126:129], v[154:157], v[186:189], v[126:129]
	v_mfma_f32_16x16x32_bf16 v[122:125], v[162:165], v[186:189], v[122:125]
	v_mfma_f32_16x16x32_bf16 v[118:121], v[154:157], v[194:197], v[118:121]
	v_mfma_f32_16x16x32_bf16 v[110:113], v[162:165], v[194:197], v[110:113]
	v_mfma_f32_16x16x32_bf16 v[102:105], v[154:157], v[202:205], v[102:105]
	v_mfma_f32_16x16x32_bf16 v[94:97], v[162:165], v[202:205], v[94:97]
	v_mfma_f32_16x16x32_bf16 v[86:89], v[154:157], v[210:213], v[86:89]
	v_mfma_f32_16x16x32_bf16 v[78:81], v[162:165], v[210:213], v[78:81]
	v_mfma_f32_16x16x32_bf16 v[126:129], v[158:161], v[190:193], v[126:129]
	v_mfma_f32_16x16x32_bf16 v[122:125], v[166:169], v[190:193], v[122:125]
	v_mfma_f32_16x16x32_bf16 v[118:121], v[158:161], v[198:201], v[118:121]
	v_mfma_f32_16x16x32_bf16 v[110:113], v[166:169], v[198:201], v[110:113]
	v_mfma_f32_16x16x32_bf16 v[102:105], v[158:161], v[206:209], v[102:105]
	v_mfma_f32_16x16x32_bf16 v[94:97], v[166:169], v[206:209], v[94:97]
	v_mfma_f32_16x16x32_bf16 v[86:89], v[158:161], v[214:217], v[86:89]
	v_mfma_f32_16x16x32_bf16 v[78:81], v[166:169], v[214:217], v[78:81]
	s_setprio 0
	s_setprio 1
	v_mfma_f32_16x16x32_bf16 v[114:117], v[170:173], v[186:189], v[114:117]
	v_mfma_f32_16x16x32_bf16 v[106:109], v[178:181], v[186:189], v[106:109]
	v_mfma_f32_16x16x32_bf16 v[98:101], v[170:173], v[194:197], v[98:101]
	v_mfma_f32_16x16x32_bf16 v[90:93], v[178:181], v[194:197], v[90:93]
	v_mfma_f32_16x16x32_bf16 v[82:85], v[170:173], v[202:205], v[82:85]
	v_mfma_f32_16x16x32_bf16 v[74:77], v[178:181], v[202:205], v[74:77]
	v_mfma_f32_16x16x32_bf16 v[70:73], v[170:173], v[210:213], v[70:73]
	v_mfma_f32_16x16x32_bf16 v[66:69], v[178:181], v[210:213], v[66:69]
	v_mfma_f32_16x16x32_bf16 v[114:117], v[174:177], v[190:193], v[114:117]
	v_mfma_f32_16x16x32_bf16 v[106:109], v[182:185], v[190:193], v[106:109]
	v_mfma_f32_16x16x32_bf16 v[98:101], v[174:177], v[198:201], v[98:101]
	v_mfma_f32_16x16x32_bf16 v[90:93], v[182:185], v[198:201], v[90:93]
	v_mfma_f32_16x16x32_bf16 v[82:85], v[174:177], v[206:209], v[82:85]
	v_mfma_f32_16x16x32_bf16 v[74:77], v[182:185], v[206:209], v[74:77]
	v_mfma_f32_16x16x32_bf16 v[70:73], v[174:177], v[214:217], v[70:73]
	v_mfma_f32_16x16x32_bf16 v[66:69], v[182:185], v[214:217], v[66:69]
	s_setprio 0
	s_barrier
	s_add_i32 s36, s66, s41
	v_lshl_add_u64 v[146:147], v[146:147], 0, s[8:9]
	s_mov_b32 m0, s36
	ds_read_b128 v[186:189], v152 offset:49152
	ds_read_b128 v[190:193], v152 offset:50176
	ds_read_b128 v[194:197], v152 offset:51200
	ds_read_b128 v[198:201], v152 offset:52224
	ds_read_b128 v[202:205], v152 offset:53248
	ds_read_b128 v[206:209], v152 offset:54272
	ds_read_b128 v[210:213], v152 offset:55296
	ds_read_b128 v[214:217], v152 offset:56320
	global_load_lds_dwordx4 v[146:147], off
	s_add_i32 m0, s36, 0x2000
	s_add_u32 s34, s34, 0x100080
	v_lshl_add_u64 v[146:147], v[218:219], 0, s[8:9]
	s_addc_u32 s35, s35, 0
	s_add_i32 s36, s67, s41
	global_load_lds_dwordx4 v[146:147], off
	v_lshl_add_u64 v[146:147], s[34:35], 0, v[132:133]
	s_mov_b32 m0, s36
	s_nop 0
	global_load_lds_dwordx4 v[146:147], off
	v_lshl_add_u64 v[146:147], s[34:35], 0, v[136:137]
	s_add_i32 m0, s36, 0x2000
	s_nop 0
	global_load_lds_dwordx4 v[146:147], off
	v_lshl_add_u64 v[146:147], v[220:221], 0, s[8:9]
	s_mov_b32 m0, s46
	s_nop 0
	global_load_lds_dwordx4 v[146:147], off
	v_lshl_add_u64 v[146:147], v[222:223], 0, s[8:9]
	s_mov_b32 m0, s47
	s_nop 0
	global_load_lds_dwordx4 v[146:147], off
	s_waitcnt vmcnt(8)
	s_waitcnt lgkmcnt(0)
	s_barrier
	s_add_i32 s65, s65, 2
	s_add_u32 s30, s30, 0x100
	s_addc_u32 s31, s31, 0
	s_add_u32 s63, s63, 0x100
	s_addc_u32 s64, s64, 0
	s_cmp_gt_u32 s65, 61
	s_setprio 1
	s_waitcnt lgkmcnt(0)
	v_mfma_f32_16x16x32_bf16 v[62:65], v[154:157], v[186:189], v[62:65]
	v_mfma_f32_16x16x32_bf16 v[58:61], v[162:165], v[186:189], v[58:61]
	v_mfma_f32_16x16x32_bf16 v[54:57], v[154:157], v[194:197], v[54:57]
	v_mfma_f32_16x16x32_bf16 v[46:49], v[162:165], v[194:197], v[46:49]
	v_mfma_f32_16x16x32_bf16 v[38:41], v[154:157], v[202:205], v[38:41]
	v_mfma_f32_16x16x32_bf16 v[30:33], v[162:165], v[202:205], v[30:33]
	v_mfma_f32_16x16x32_bf16 v[22:25], v[154:157], v[210:213], v[22:25]
	v_mfma_f32_16x16x32_bf16 v[14:17], v[162:165], v[210:213], v[14:17]
	v_mfma_f32_16x16x32_bf16 v[62:65], v[158:161], v[190:193], v[62:65]
	v_mfma_f32_16x16x32_bf16 v[58:61], v[166:169], v[190:193], v[58:61]
	v_mfma_f32_16x16x32_bf16 v[54:57], v[158:161], v[198:201], v[54:57]
	v_mfma_f32_16x16x32_bf16 v[46:49], v[166:169], v[198:201], v[46:49]
	v_mfma_f32_16x16x32_bf16 v[38:41], v[158:161], v[206:209], v[38:41]
	v_mfma_f32_16x16x32_bf16 v[30:33], v[166:169], v[206:209], v[30:33]
	v_mfma_f32_16x16x32_bf16 v[22:25], v[158:161], v[214:217], v[22:25]
	v_mfma_f32_16x16x32_bf16 v[14:17], v[166:169], v[214:217], v[14:17]
	s_setprio 0
	s_setprio 1
	v_mfma_f32_16x16x32_bf16 v[50:53], v[170:173], v[186:189], v[50:53]
	v_mfma_f32_16x16x32_bf16 v[42:45], v[178:181], v[186:189], v[42:45]
	v_mfma_f32_16x16x32_bf16 v[34:37], v[170:173], v[194:197], v[34:37]
	v_mfma_f32_16x16x32_bf16 v[26:29], v[178:181], v[194:197], v[26:29]
	v_mfma_f32_16x16x32_bf16 v[18:21], v[170:173], v[202:205], v[18:21]
	v_mfma_f32_16x16x32_bf16 v[10:13], v[178:181], v[202:205], v[10:13]
	v_mfma_f32_16x16x32_bf16 v[6:9], v[170:173], v[210:213], v[6:9]
	v_mfma_f32_16x16x32_bf16 v[2:5], v[178:181], v[210:213], v[2:5]
	v_mfma_f32_16x16x32_bf16 v[50:53], v[174:177], v[190:193], v[50:53]
	v_mfma_f32_16x16x32_bf16 v[42:45], v[182:185], v[190:193], v[42:45]
	v_mfma_f32_16x16x32_bf16 v[34:37], v[174:177], v[198:201], v[34:37]
	v_mfma_f32_16x16x32_bf16 v[26:29], v[182:185], v[198:201], v[26:29]
	v_mfma_f32_16x16x32_bf16 v[18:21], v[174:177], v[206:209], v[18:21]
	v_mfma_f32_16x16x32_bf16 v[10:13], v[182:185], v[206:209], v[10:13]
	v_mfma_f32_16x16x32_bf16 v[6:9], v[174:177], v[214:217], v[6:9]
	v_mfma_f32_16x16x32_bf16 v[2:5], v[182:185], v[214:217], v[2:5]
	s_setprio 0
	s_barrier
	s_cbranch_scc0 .LBB0_1241
	s_and_b64 vcc, exec, s[10:11]
	s_cbranch_vccz .LBB0_1244
	s_barrier
